# DA ping-pong: split inside softmax (after 24 exp/sum ops), QK-only priority, 4-bit K swizzle, softmax head with split max chains and all-lanes fast path, PV prefetch depth 4
# speedup vs baseline: 1.0340x; 1.0172x over previous
; __device__ __forceinline__ int v_rd_base(int lane) { return ((lane & 3) << 3) | (((lane >> 2) & 3) << 6) | (((lane >> 4) & 1) << 5) | (((lane >> 5) & 1) << 8); }
; #define DPUB() do { asm volatile("s_waitcnt vmcnt(0)" ::: "memory"); __syncthreads(); } while (0)
; __device__ __forceinline__ void unit_body_da(const Unit& U, char* lds) {
;   int tid = threadIdx.x; asm volatile("" : "+v"(tid)); const int wid = __builtin_amdgcn_readfirstlane(tid >> 6), lane = tid & 63, r32 = lane & 31, hi = lane >> 5;
;   char* V_lds = lds; char* K_lds = lds + 2 * DA_VB;
;   float* ws = (float*)(lds + DA_WS_OFF) + wid * 64; float* li_l = ws; float* al_l = ws + 32;
;   float m_reg = -1e30f, l_reg = 0; f32x16 o[8] = {}; bf16x8 qr[8];
;   const bf16_t* Qw = U.Q + (long)(wid * QBLK + r32) * LDP + hi * 8;
; #pragma unroll
;   for (int d0 = 0; d0 < 8; ++d0) qr[d0] = ld8(Qw + d0 * 16);
;   const int vb0 = (int)(uintptr_t)V_lds + v_rd_base(lane);
;   const int ka0 = (int)(uintptr_t)K_lds + KSWZ(r32, hi * 16);
;   constexpr float C = SCALE * 1.4426950408889634f;
;   unsigned koff[2], voff[2][2];
; #pragma unroll
;   for (int i = 0; i < 2; ++i) { const int ob = (2 * wid + i) * 1024 + lane * 16;
;     { const int row = ob >> 8, cpos = (ob >> 4) & 15, c = cpos ^ (row & 7); koff[i] = (unsigned)(row * LDP + c * 8); }
;     { const int st = ob >> 9, kk = (st >> 2) * 8 + ((ob >> 6) & 7), c = (st & 3) * 32 + ((ob >> 1) & 31), k = (kk & ~0xC) | ((kk & 4) << 1) | ((kk & 8) >> 1);
;       voff[0][i] = (unsigned)(k * LDP + c); voff[1][i] = (unsigned)(k * LDP + 128 + c); } }
;   typedef __attribute__((address_space(3))) unsigned lds_u32;
;     ...
;   const int NT = U.nt;
;   DDMA(0, 0); DPUB();
.LBB0_426:
	s_cbranch_execz .LBB0_370
	v_mov_b32_e32 v8, v210
	v_mov_b64_e32 v[2:3], s[58:59]
	v_readfirstlane_b32 s3, v8
	s_ashr_i32 s6, s3, 6
	s_and_b32 s3, s3, 0x3fffffc0
	s_lshl_b32 s3, s3, 2
	v_and_b32_e32 v234, 31, v8
	s_add_i32 s24, s3, 0
	s_lshl_b32 s64, s6, 5
	v_bfe_u32 v233, v8, 5, 1
	s_add_i32 s24, s24, 0x18000
	v_or_b32_e32 v0, s64, v234
	s_add_i32 s67, 0, 0x10000
	v_mad_i64_i32 v[2:3], s[4:5], v0, s96, v[2:3]
	v_lshlrev_b32_e32 v212, 4, v233
	v_mov_b32_e32 v213, v1
	s_cmp_lg_u32 s67, -1
	v_lshl_add_u64 v[2:3], v[2:3], 0, v[212:213]
	s_cselect_b32 s3, s67, 0
	s_lshl_b32 s25, s6, 11
	global_load_dwordx4 v[162:165], v[2:3], off
	global_load_dwordx4 v[166:169], v[2:3], off offset:32
	global_load_dwordx4 v[170:173], v[2:3], off offset:64
	global_load_dwordx4 v[174:177], v[2:3], off offset:96
	global_load_dwordx4 v[178:181], v[2:3], off offset:128
	global_load_dwordx4 v[182:185], v[2:3], off offset:160
	global_load_dwordx4 v[186:189], v[2:3], off offset:192
	global_load_dwordx4 v[190:193], v[2:3], off offset:224
	s_ashr_i32 s4, s25, 8
	v_lshrrev_b32_e32 v2, 1, v8
	v_and_b32_e32 v9, 63, v8
	v_bfe_u32 v0, v8, 2, 2
	s_and_b32 s5, s4, 0xfffff0
	v_and_b32_e32 v2, 8, v2
	v_lshlrev_b32_e32 v12, 4, v9
	s_lshr_b32 s4, s4, 1
	v_or3_b32 v0, v2, v0, s5
	v_and_or_b32 v0, s4, 4, v0
	v_or_b32_e32 v5, 0x400, v12
	v_mul_i32_i24_e32 v13, 0x1800, v0
	v_or_b32_e32 v0, s25, v12
	v_or_b32_e32 v4, s25, v5
	v_and_b32_e32 v3, 15, v8
	v_ashrrev_i32_e32 v0, 8, v0
	v_ashrrev_i32_e32 v4, 8, v4
	v_bitop3_b32 v2, v0, v3, 15 bitop3:0x6c
	v_bitop3_b32 v3, v4, v3, 15 bitop3:0x6c
	v_mul_i32_i24_e32 v4, 0x1800, v4
	v_lshlrev_b32_e32 v10, 3, v9
	v_mul_i32_i24_e32 v0, 0x1800, v0
	v_lshl_or_b32 v4, v3, 3, v4
	v_lshrrev_b32_e32 v3, 4, v5
	v_and_b32_e32 v11, 24, v10
	v_lshl_or_b32 v0, v2, 3, v0
	v_and_b32_e32 v14, 32, v8
	v_and_b32_e32 v3, 0x60, v3
	s_add_i32 s28, s67, s25
	v_or3_b32 v2, v11, v14, v13
	v_or3_b32 v6, v11, v3, v13
	v_lshl_add_u64 v[214:215], v[0:1], 1, s[46:47]
	s_mov_b32 m0, s28
	v_mov_b32_e32 v3, v1
	s_add_i32 s29, s25, 0
	global_load_lds_dwordx4 v[214:215], off
	v_lshl_add_u64 v[2:3], v[2:3], 1, s[22:23]
	s_mov_b32 m0, s29
	s_mov_b64 s[4:5], 0x100
	s_add_i32 s65, s29, 0x4000
	s_or_b32 s66, s25, 0x400
	global_load_lds_dwordx4 v[2:3], off
	v_lshl_add_u64 v[2:3], v[2:3], 0, s[4:5]
	s_mov_b32 m0, s65
	v_mov_b32_e32 v5, v1
	s_add_i32 s67, s67, s66
	global_load_lds_dwordx4 v[2:3], off
	v_lshl_add_u64 v[216:217], v[4:5], 1, s[46:47]
	s_mov_b32 m0, s67
	v_mov_b32_e32 v7, v1
	s_add_i32 s68, s29, 0x400
	global_load_lds_dwordx4 v[216:217], off
	v_lshl_add_u64 v[2:3], v[6:7], 1, s[22:23]
	s_mov_b32 m0, s68
	s_add_i32 s69, s29, 0x4400
	global_load_lds_dwordx4 v[2:3], off
	v_lshl_add_u64 v[2:3], v[2:3], 0, s[4:5]
	s_mov_b32 m0, s69
	v_lshlrev_b32_e32 v0, 1, v8
	global_load_lds_dwordx4 v[2:3], off
	v_and_b32_e32 v0, 32, v0
	v_and_or_b32 v0, v12, s97, v0
	v_and_b32_e32 v2, 0x100, v10
	s_cmp_lg_u32 0, -1
	v_or3_b32 v0, v0, v2, v11
	v_bitop3_b32 v3, v233, v8, 15 bitop3:0x78
	s_cselect_b32 s6, 0, 0
	v_lshlrev_b32_e32 v2, 8, v234
	v_lshlrev_b32_e32 v3, 4, v3
	v_add_u32_e32 v213, s6, v0
	s_add_i32 s6, s6, 0x8000
	v_add3_u32 v235, v2, s3, v3
	v_add_u32_e32 v244, s6, v0
	v_or3_b32 v0, v13, v14, v11
	s_movk_i32 s3, 0x60
	v_lshl_add_u64 v[218:219], v[0:1], 1, s[22:23]
	v_bitop3_b32 v0, v9, s3, 64 bitop3:0xc8
	v_or3_b32 v0, v13, v0, v11
	v_mov_b32_e32 v14, v1
	v_mov_b32_e32 v15, v1
	s_waitcnt vmcnt(0)
	v_cmp_gt_u32_e64 s[4:5], 32, v9
	v_lshl_add_u64 v[220:221], v[0:1], 1, s[22:23]
	v_mov_b32_e32 v0, v1
	v_mov_b32_e32 v2, v1
	v_mov_b32_e32 v3, v1
	v_mov_b32_e32 v4, v1
	v_mov_b32_e32 v6, v1
	v_mov_b32_e32 v8, v1
	v_mov_b32_e32 v9, v1
	v_mov_b32_e32 v10, v1
	v_mov_b32_e32 v11, v1
	v_mov_b32_e32 v12, v1
	v_mov_b32_e32 v13, v1
	v_mov_b64_e32 v[128:129], v[14:15]
	v_mov_b64_e32 v[112:113], v[14:15]
	v_mov_b64_e32 v[96:97], v[14:15]
	v_mov_b64_e32 v[80:81], v[14:15]
	v_mov_b64_e32 v[64:65], v[14:15]
	v_mov_b64_e32 v[48:49], v[14:15]
	v_mov_b64_e32 v[32:33], v[14:15]
	v_mov_b64_e32 v[126:127], v[12:13]
	v_mov_b64_e32 v[124:125], v[10:11]
	v_mov_b64_e32 v[122:123], v[8:9]
	v_mov_b64_e32 v[120:121], v[6:7]
	v_mov_b64_e32 v[118:119], v[4:5]
	v_mov_b64_e32 v[116:117], v[2:3]
	v_mov_b64_e32 v[114:115], v[0:1]
	v_mov_b64_e32 v[110:111], v[12:13]
	v_mov_b64_e32 v[108:109], v[10:11]
	v_mov_b64_e32 v[106:107], v[8:9]
	v_mov_b64_e32 v[104:105], v[6:7]
	v_mov_b64_e32 v[102:103], v[4:5]
	v_mov_b64_e32 v[100:101], v[2:3]
	v_mov_b64_e32 v[98:99], v[0:1]
	v_mov_b64_e32 v[94:95], v[12:13]
	v_mov_b64_e32 v[92:93], v[10:11]
	v_mov_b64_e32 v[90:91], v[8:9]
	v_mov_b64_e32 v[88:89], v[6:7]
	v_mov_b64_e32 v[86:87], v[4:5]
	v_mov_b64_e32 v[84:85], v[2:3]
	v_mov_b64_e32 v[82:83], v[0:1]
	v_mov_b64_e32 v[78:79], v[12:13]
	v_mov_b64_e32 v[76:77], v[10:11]
	v_mov_b64_e32 v[74:75], v[8:9]
	v_mov_b64_e32 v[72:73], v[6:7]
	v_mov_b64_e32 v[70:71], v[4:5]
	v_mov_b64_e32 v[68:69], v[2:3]
	v_mov_b64_e32 v[66:67], v[0:1]
	v_mov_b64_e32 v[62:63], v[12:13]
	v_mov_b64_e32 v[60:61], v[10:11]
	v_mov_b64_e32 v[58:59], v[8:9]
	v_mov_b64_e32 v[56:57], v[6:7]
	v_mov_b64_e32 v[54:55], v[4:5]
	v_mov_b64_e32 v[52:53], v[2:3]
	v_mov_b64_e32 v[50:51], v[0:1]
	v_mov_b64_e32 v[46:47], v[12:13]
	v_mov_b64_e32 v[44:45], v[10:11]
	v_mov_b64_e32 v[42:43], v[8:9]
	v_mov_b64_e32 v[40:41], v[6:7]
	v_mov_b64_e32 v[38:39], v[4:5]
	v_mov_b64_e32 v[36:37], v[2:3]
	v_mov_b64_e32 v[34:35], v[0:1]
	v_mov_b64_e32 v[30:31], v[12:13]
	v_mov_b64_e32 v[28:29], v[10:11]
	v_mov_b64_e32 v[26:27], v[8:9]
	v_mov_b64_e32 v[24:25], v[6:7]
	v_mov_b64_e32 v[22:23], v[4:5]
	v_mov_b64_e32 v[20:21], v[2:3]
	v_mov_b64_e32 v[18:19], v[0:1]
	v_mov_b64_e32 v[16:17], v[14:15]
	s_mov_b32 s80, 2
	v_xor_b32_e32 v236, 32, v235
	v_xor_b32_e32 v238, 64, v235
	v_xor_b32_e32 v239, 0x60, v235
	v_xor_b32_e32 v240, 0x80, v235
	v_xor_b32_e32 v241, 0xa0, v235
	v_xor_b32_e32 v242, 0xc0, v235
	v_xor_b32_e32 v243, 0xe0, v235
	v_lshl_add_u32 v237, v234, 2, s24
	v_mov_b32_e32 v245, 0
	v_mov_b32_e32 v246, 0xf149f2ca
	s_mov_b64 s[22:23], 0
	v_mov_b64_e32 v[14:15], v[12:13]
	v_mov_b64_e32 v[12:13], v[10:11]
	v_mov_b64_e32 v[10:11], v[8:9]
	v_mov_b64_e32 v[8:9], v[6:7]
	v_mov_b64_e32 v[6:7], v[4:5]
	v_mov_b64_e32 v[4:5], v[2:3]
	v_mov_b64_e32 v[2:3], v[0:1]
	s_waitcnt vmcnt(0) lgkmcnt(0)
	s_barrier
	s_cmp_lt_u32 s25, 0x2000
	s_cbranch_scc1 .Lda_l0_lead_in
	s_barrier

; #define SBAR() __builtin_amdgcn_sched_barrier(0)
; __device__ __forceinline__ void partialSM(f32x16& p0, f32x16& p1, float& m_reg, float& mn, float& alpha) {
;     ...
;   float mnC = -mn * C;
; #pragma unroll
;   for (int r = 0; r < 16; ++r) p0[r] = fmaf(p0[r], C, mnC);
; #pragma unroll
;   for (int r = 0; r < 16; ++r) p1[r] = fmaf(p1[r], C, mnC);
; #pragma unroll
;   for (int r = 0; r < 16; ++r) p0[r] = __builtin_amdgcn_exp2f(p0[r]);
; }
; __device__ __forceinline__ void finishSM(f32x16& p0, f32x16& p1, float alpha, float& l_reg, bf16x8& pa0, bf16x8& pa1, bf16x8& pa2, bf16x8& pa3) {
; #pragma unroll
;   for (int r = 0; r < 16; ++r) p1[r] = __builtin_amdgcn_exp2f(p1[r]);
;   float ps = 0;
; #pragma unroll
;   for (int r = 0; r < 16; ++r) ps += p0[r];
; #pragma unroll
;   for (int r = 0; r < 16; ++r) ps += p1[r];
;   { auto rr = __builtin_amdgcn_permlane32_swap(__float_as_uint(ps), __float_as_uint(ps), false, false);
;     ps = __uint_as_float(rr[0]) + __uint_as_float(rr[1]); }
;   l_reg = l_reg * alpha + ps;
;     ...
;   PK4(p0, 0, pa0); PK4(p0, 8, pa1); PK4(p1, 0, pa2); PK4(p1, 8, pa3);
;     ...
; }
; template <int I> __device__ __forceinline__ void pv_step(f32x16* o, int vb, const bf16x8 (&pa)[4], s16x4 (&l)[3], s16x4 (&h)[3]) {
;   if constexpr (I + 2 < 32) pv_rd<(I + 2 < 32 ? I + 2 : 0)>(vb, l[(I + 2) % 3], h[(I + 2) % 3]);
;   if constexpr (I + 2 < 32) asm volatile("s_waitcnt lgkmcnt(4)" ::: "memory"); else if constexpr (I + 1 < 32) asm volatile("s_waitcnt lgkmcnt(2)" ::: "memory"); else asm volatile("s_waitcnt lgkmcnt(0)" ::: "memory");
;   SBAR();
;   const s16x4 L = l[I % 3], H = h[I % 3];
;   o[I >> 2] = __builtin_amdgcn_mfma_f32_32x32x16_bf16(pa[I & 3], (bf16x8){L[0], L[1], L[2], L[3], H[0], H[1], H[2], H[3]}, o[I >> 2], 0, 0, 0);
;   SBAR();
;   if constexpr (I + 1 < 32) pv_step<(I + 1 < 32 ? I + 1 : 31)>(o, vb, pa, l, h);
; }
; __device__ __forceinline__ void pv_all_rolling(f32x16* o, int vb, bf16x8 pa0, bf16x8 pa1, bf16x8 pa2, bf16x8 pa3) {
;   const bf16x8 pa[4] = {pa0, pa1, pa2, pa3}; s16x4 l[3], h[3];
;   asm volatile("s_waitcnt lgkmcnt(0)" ::: "memory");
;   pv_rd<0>(vb, l[0], h[0]); pv_rd<1>(vb, l[1], h[1]);
;   pv_step<0>(o, vb, pa, l, h);
.LBB0_429:
	v_cndmask_b32_e64 v246, v223, v246, s[6:7]
	v_mul_f32_e32 v194, 0xbe0293ee, v246
	v_fmamk_f32 v146, v146, 0x3e0293ee, v194
	v_fmamk_f32 v147, v147, 0x3e0293ee, v194
	v_fmamk_f32 v148, v148, 0x3e0293ee, v194
	v_fmamk_f32 v149, v149, 0x3e0293ee, v194
	v_fmamk_f32 v150, v150, 0x3e0293ee, v194
	v_fmamk_f32 v151, v151, 0x3e0293ee, v194
	v_fmamk_f32 v152, v152, 0x3e0293ee, v194
	v_fmamk_f32 v153, v153, 0x3e0293ee, v194
	v_fmamk_f32 v154, v154, 0x3e0293ee, v194
	v_fmamk_f32 v155, v155, 0x3e0293ee, v194
	v_fmamk_f32 v156, v156, 0x3e0293ee, v194
	v_fmamk_f32 v157, v157, 0x3e0293ee, v194
	v_fmamk_f32 v158, v158, 0x3e0293ee, v194
	v_fmamk_f32 v159, v159, 0x3e0293ee, v194
	v_fmamk_f32 v160, v160, 0x3e0293ee, v194
	v_fmamk_f32 v161, v161, 0x3e0293ee, v194
	v_fmamk_f32 v130, v130, 0x3e0293ee, v194
	v_fmamk_f32 v131, v131, 0x3e0293ee, v194
	v_fmamk_f32 v132, v132, 0x3e0293ee, v194
	v_fmamk_f32 v133, v133, 0x3e0293ee, v194
	v_fmamk_f32 v134, v134, 0x3e0293ee, v194
	v_fmamk_f32 v135, v135, 0x3e0293ee, v194
	v_fmamk_f32 v136, v136, 0x3e0293ee, v194
	v_fmamk_f32 v137, v137, 0x3e0293ee, v194
	v_fmamk_f32 v138, v138, 0x3e0293ee, v194
	v_fmamk_f32 v139, v139, 0x3e0293ee, v194
	v_fmamk_f32 v140, v140, 0x3e0293ee, v194
	v_fmamk_f32 v141, v141, 0x3e0293ee, v194
	v_fmamk_f32 v142, v142, 0x3e0293ee, v194
	v_fmamk_f32 v143, v143, 0x3e0293ee, v194
	v_fmamk_f32 v144, v144, 0x3e0293ee, v194
	v_fmac_f32_e32 v194, 0x3e0293ee, v145
	v_exp_f32_e32 v145, v146
	v_exp_f32_e32 v146, v147
	v_exp_f32_e32 v147, v148
	v_exp_f32_e32 v148, v149
	v_exp_f32_e32 v149, v150
	v_exp_f32_e32 v150, v151
	v_exp_f32_e32 v151, v152
	v_exp_f32_e32 v152, v153
	v_exp_f32_e32 v153, v154
	v_exp_f32_e32 v154, v155
	v_exp_f32_e32 v155, v156
	v_exp_f32_e32 v156, v157
	v_exp_f32_e32 v157, v158
	v_exp_f32_e32 v158, v159
	v_exp_f32_e32 v159, v160
	v_exp_f32_e32 v160, v161
	v_add_f32_e32 v161, v247, v248
	v_fmac_f32_e32 v161, v245, v0
	v_exp_f32_e32 v0, v130
	v_add_f32_e32 v130, 0, v145
	v_add_f32_e32 v130, v146, v130
	v_add_f32_e32 v130, v147, v130
	v_add_f32_e32 v130, v148, v130
	v_add_f32_e32 v130, v149, v130
	s_waitcnt vmcnt(0)
	s_barrier
	s_setprio 0
	v_add_f32_e32 v130, v150, v130
	v_add_f32_e32 v130, v151, v130
	v_add_f32_e32 v130, v152, v130
	v_add_f32_e32 v130, v153, v130
	v_add_f32_e32 v130, v154, v130
	v_add_f32_e32 v130, v155, v130
	v_add_f32_e32 v130, v156, v130
	v_add_f32_e32 v130, v157, v130
	v_exp_f32_e32 v195, v131
	v_add_f32_e32 v130, v158, v130
	v_exp_f32_e32 v196, v132
	v_add_f32_e32 v130, v159, v130
	v_exp_f32_e32 v197, v133
	v_add_f32_e32 v130, v160, v130
	v_exp_f32_e32 v198, v134
	v_add_f32_e32 v130, v0, v130
	v_exp_f32_e32 v199, v135
	v_add_f32_e32 v130, v195, v130
	v_exp_f32_e32 v200, v136
	v_add_f32_e32 v130, v196, v130
	v_exp_f32_e32 v201, v137
	v_add_f32_e32 v130, v197, v130
	v_exp_f32_e32 v202, v138
	v_add_f32_e32 v130, v198, v130
	v_exp_f32_e32 v203, v139
	v_add_f32_e32 v130, v199, v130
	v_exp_f32_e32 v204, v140
	v_add_f32_e32 v130, v200, v130
	v_exp_f32_e32 v205, v141
	v_add_f32_e32 v130, v201, v130
	v_exp_f32_e32 v206, v142
	v_add_f32_e32 v130, v202, v130
	v_exp_f32_e32 v207, v143
	v_add_f32_e32 v130, v203, v130
	v_exp_f32_e32 v208, v144
	v_add_f32_e32 v130, v204, v130
	v_exp_f32_e32 v194, v194
	v_add_f32_e32 v130, v205, v130
	v_add_f32_e32 v130, v206, v130
	v_add_f32_e32 v130, v207, v130
	v_add_f32_e32 v130, v208, v130
	v_add_f32_e32 v130, v194, v130
	v_mov_b32_e32 v131, v130
	s_nop 1
	v_permlane32_swap_b32_e32 v130, v131
	v_add_f32_e32 v245, v130, v131
	v_fmac_f32_e32 v245, v161, v222
	v_cvt_pk_bf16_f32 v130, v145, v146
	v_cvt_pk_bf16_f32 v131, v147, v148
	v_cvt_pk_bf16_f32 v132, v149, v150
	v_cvt_pk_bf16_f32 v133, v151, v152
	v_cvt_pk_bf16_f32 v134, v153, v154
	v_cvt_pk_bf16_f32 v135, v155, v156
	v_cvt_pk_bf16_f32 v136, v157, v158
	v_cvt_pk_bf16_f32 v137, v159, v160
	v_cvt_pk_bf16_f32 v138, v0, v195
	v_cvt_pk_bf16_f32 v139, v196, v197
	v_cvt_pk_bf16_f32 v140, v198, v199
	v_cvt_pk_bf16_f32 v141, v200, v201
	v_cvt_pk_bf16_f32 v142, v202, v203
	v_cvt_pk_bf16_f32 v143, v204, v205
	v_cvt_pk_bf16_f32 v144, v206, v207
	v_cvt_pk_bf16_f32 v145, v208, v194
	s_nop 0
	v_permlane32_swap_b32_e32 v130, v132
	v_permlane32_swap_b32_e32 v131, v133
	v_permlane32_swap_b32_e32 v134, v136
	v_permlane32_swap_b32_e32 v135, v137
	v_permlane32_swap_b32_e32 v138, v140
	v_permlane32_swap_b32_e32 v139, v141
	v_permlane32_swap_b32_e32 v142, v144
	v_permlane32_swap_b32_e32 v143, v145
	s_waitcnt lgkmcnt(0)
	ds_read_b64_tr_b16 v[146:147], v244 offset:0
	ds_read_b64_tr_b16 v[148:149], v244 offset:2048
	ds_read_b64_tr_b16 v[150:151], v244 offset:4096
	ds_read_b64_tr_b16 v[152:153], v244 offset:6144
	ds_read_b64_tr_b16 v[154:155], v244 offset:8192
	ds_read_b64_tr_b16 v[156:157], v244 offset:10240
	ds_read_b64_tr_b16 v[158:159], v244 offset:12288
	ds_read_b64_tr_b16 v[160:161], v244 offset:14336
	ds_read_b64_tr_b16 v[194:195], v244 offset:512
	ds_read_b64_tr_b16 v[196:197], v244 offset:2560
	v_lshl_add_u64 v[232:233], v[218:219], 0, s[22:23]
	v_lshl_add_u64 v[232:233], v[232:233], 0, s[14:15]
	s_mov_b32 m0, s29
	s_nop 0
	global_load_lds_dwordx4 v[232:233], off
	s_waitcnt lgkmcnt(8)
	s_nop 0
	v_mfma_f32_32x32x16_bf16 v[114:129], v[130:133], v[146:149], v[114:129]
	ds_read_b64_tr_b16 v[198:199], v244 offset:4608
	ds_read_b64_tr_b16 v[200:201], v244 offset:6656
	v_lshl_add_u64 v[232:233], v[218:219], 0, s[22:23]
	v_lshl_add_u64 v[232:233], v[232:233], 0, s[16:17]
	s_mov_b32 m0, s65
	s_nop 0
	global_load_lds_dwordx4 v[232:233], off
	s_waitcnt lgkmcnt(8)
; #define SBAR() __builtin_amdgcn_sched_barrier(0)
; #define DPUB() do { asm volatile("s_waitcnt vmcnt(0)" ::: "memory"); __syncthreads(); } while (0)
; #define DTILE(b) do { f32x16 p0 = f32x16{}, p1 = f32x16{}; float mn, al; bf16x8 pa0, pa1, pa2, pa3; \
;     qkt_rolling<(b) * DA_KB>(p0, p1, ka0, qr); partialSM(p0, p1, m_reg, mn, al); DRESC(al); finishSM(p0, p1, al, l_reg, pa0, pa1, pa2, pa3); SBAR(); \
;     pv_all_rolling(o, vb0 + (b) * DA_VB, pa0, pa1, pa2, pa3); } while (0)
; template <int I> __device__ __forceinline__ void pv_step(f32x16* o, int vb, const bf16x8 (&pa)[4], s16x4 (&l)[3], s16x4 (&h)[3]) {
;   if constexpr (I + 2 < 32) pv_rd<(I + 2 < 32 ? I + 2 : 0)>(vb, l[(I + 2) % 3], h[(I + 2) % 3]);
;   if constexpr (I + 2 < 32) asm volatile("s_waitcnt lgkmcnt(4)" ::: "memory"); else if constexpr (I + 1 < 32) asm volatile("s_waitcnt lgkmcnt(2)" ::: "memory"); else asm volatile("s_waitcnt lgkmcnt(0)" ::: "memory");
;   SBAR();
;   const s16x4 L = l[I % 3], H = h[I % 3];
;   o[I >> 2] = __builtin_amdgcn_mfma_f32_32x32x16_bf16(pa[I & 3], (bf16x8){L[0], L[1], L[2], L[3], H[0], H[1], H[2], H[3]}, o[I >> 2], 0, 0, 0);
;   SBAR();
;   if constexpr (I + 1 < 32) pv_step<(I + 1 < 32 ? I + 1 : 31)>(o, vb, pa, l, h);
; }
; __device__ __forceinline__ void pv_all_rolling(f32x16* o, int vb, bf16x8 pa0, bf16x8 pa1, bf16x8 pa2, bf16x8 pa3) {
;   const bf16x8 pa[4] = {pa0, pa1, pa2, pa3}; s16x4 l[3], h[3];
;   asm volatile("s_waitcnt lgkmcnt(0)" ::: "memory");
;   pv_rd<0>(vb, l[0], h[0]); pv_rd<1>(vb, l[1], h[1]);
;   pv_step<0>(o, vb, pa, l, h);
; __device__ __forceinline__ void unit_body_da(const Unit& U, char* lds) {
;     ...
;   for (int j = 0; j < NT; j += 2) {
;     DDMA(j + 1, 1); SBAR();
;     DTILE(0); SBAR(); DPUB();
;     if (j + 2 < NT) DDMA(j + 2, 0); SBAR();
;     DTILE(1); SBAR(); DPUB();
;   }
	v_mfma_f32_32x32x16_bf16 v[114:129], v[134:137], v[150:153], v[114:129]
	ds_read_b64_tr_b16 v[202:203], v244 offset:8704
	ds_read_b64_tr_b16 v[204:205], v244 offset:10752
	v_lshl_add_u64 v[232:233], v[220:221], 0, s[22:23]
	v_lshl_add_u64 v[232:233], v[232:233], 0, s[14:15]
	s_mov_b32 m0, s68
	s_nop 0
	global_load_lds_dwordx4 v[232:233], off
	s_waitcnt lgkmcnt(8)
	v_mfma_f32_32x32x16_bf16 v[114:129], v[138:141], v[154:157], v[114:129]
	ds_read_b64_tr_b16 v[206:207], v244 offset:12800
	ds_read_b64_tr_b16 v[208:209], v244 offset:14848
	v_lshl_add_u64 v[232:233], v[220:221], 0, s[22:23]
	v_lshl_add_u64 v[232:233], v[232:233], 0, s[16:17]
	s_mov_b32 m0, s69
	s_nop 0
	global_load_lds_dwordx4 v[232:233], off
	s_waitcnt lgkmcnt(8)
	v_mfma_f32_32x32x16_bf16 v[114:129], v[142:145], v[158:161], v[114:129]
	ds_read_b64_tr_b16 v[146:147], v244 offset:1024
	ds_read_b64_tr_b16 v[148:149], v244 offset:3072
	s_waitcnt lgkmcnt(8)
	v_mfma_f32_32x32x16_bf16 v[98:113], v[130:133], v[194:197], v[98:113]
	ds_read_b64_tr_b16 v[150:151], v244 offset:5120
	ds_read_b64_tr_b16 v[152:153], v244 offset:7168
	s_waitcnt lgkmcnt(8)
	v_mfma_f32_32x32x16_bf16 v[98:113], v[134:137], v[198:201], v[98:113]
	ds_read_b64_tr_b16 v[154:155], v244 offset:9216
	ds_read_b64_tr_b16 v[156:157], v244 offset:11264
	s_waitcnt lgkmcnt(8)
	v_mfma_f32_32x32x16_bf16 v[98:113], v[138:141], v[202:205], v[98:113]
	ds_read_b64_tr_b16 v[158:159], v244 offset:13312
	ds_read_b64_tr_b16 v[160:161], v244 offset:15360
	s_waitcnt lgkmcnt(8)
	v_mfma_f32_32x32x16_bf16 v[98:113], v[142:145], v[206:209], v[98:113]
	ds_read_b64_tr_b16 v[194:195], v244 offset:1536
	ds_read_b64_tr_b16 v[196:197], v244 offset:3584
	s_waitcnt lgkmcnt(8)
	v_mfma_f32_32x32x16_bf16 v[82:97], v[130:133], v[146:149], v[82:97]
	ds_read_b64_tr_b16 v[198:199], v244 offset:5632
	ds_read_b64_tr_b16 v[200:201], v244 offset:7680
	s_waitcnt lgkmcnt(8)
	v_mfma_f32_32x32x16_bf16 v[82:97], v[134:137], v[150:153], v[82:97]
	ds_read_b64_tr_b16 v[202:203], v244 offset:9728
	ds_read_b64_tr_b16 v[204:205], v244 offset:11776
	s_waitcnt lgkmcnt(8)
	v_mfma_f32_32x32x16_bf16 v[82:97], v[138:141], v[154:157], v[82:97]
	ds_read_b64_tr_b16 v[206:207], v244 offset:13824
	ds_read_b64_tr_b16 v[208:209], v244 offset:15872
	s_waitcnt lgkmcnt(8)
	v_mfma_f32_32x32x16_bf16 v[82:97], v[142:145], v[158:161], v[82:97]
	ds_read_b64_tr_b16 v[146:147], v244 offset:16384
	ds_read_b64_tr_b16 v[148:149], v244 offset:18432
	s_waitcnt lgkmcnt(8)
	v_mfma_f32_32x32x16_bf16 v[66:81], v[130:133], v[194:197], v[66:81]
	ds_read_b64_tr_b16 v[150:151], v244 offset:20480
	ds_read_b64_tr_b16 v[152:153], v244 offset:22528
	s_waitcnt lgkmcnt(8)
	v_mfma_f32_32x32x16_bf16 v[66:81], v[134:137], v[198:201], v[66:81]
	ds_read_b64_tr_b16 v[154:155], v244 offset:24576
	ds_read_b64_tr_b16 v[156:157], v244 offset:26624
	s_waitcnt lgkmcnt(8)
	v_mfma_f32_32x32x16_bf16 v[66:81], v[138:141], v[202:205], v[66:81]
	ds_read_b64_tr_b16 v[158:159], v244 offset:28672
	ds_read_b64_tr_b16 v[160:161], v244 offset:30720
	s_waitcnt lgkmcnt(8)
	v_mfma_f32_32x32x16_bf16 v[66:81], v[142:145], v[206:209], v[66:81]
	ds_read_b64_tr_b16 v[194:195], v244 offset:16896
	ds_read_b64_tr_b16 v[196:197], v244 offset:18944
	s_waitcnt lgkmcnt(8)
	v_mfma_f32_32x32x16_bf16 v[50:65], v[130:133], v[146:149], v[50:65]
	ds_read_b64_tr_b16 v[198:199], v244 offset:20992
	ds_read_b64_tr_b16 v[200:201], v244 offset:23040
	s_waitcnt lgkmcnt(8)
	v_mfma_f32_32x32x16_bf16 v[50:65], v[134:137], v[150:153], v[50:65]
	ds_read_b64_tr_b16 v[202:203], v244 offset:25088
	ds_read_b64_tr_b16 v[204:205], v244 offset:27136
	s_waitcnt lgkmcnt(8)
	v_mfma_f32_32x32x16_bf16 v[50:65], v[138:141], v[154:157], v[50:65]
	ds_read_b64_tr_b16 v[206:207], v244 offset:29184
	ds_read_b64_tr_b16 v[208:209], v244 offset:31232
	s_waitcnt lgkmcnt(8)
	v_mfma_f32_32x32x16_bf16 v[50:65], v[142:145], v[158:161], v[50:65]
	ds_read_b64_tr_b16 v[146:147], v244 offset:17408
	ds_read_b64_tr_b16 v[148:149], v244 offset:19456
	s_waitcnt lgkmcnt(8)
	v_mfma_f32_32x32x16_bf16 v[34:49], v[130:133], v[194:197], v[34:49]
	ds_read_b64_tr_b16 v[150:151], v244 offset:21504
	ds_read_b64_tr_b16 v[152:153], v244 offset:23552
	s_waitcnt lgkmcnt(8)
	v_mfma_f32_32x32x16_bf16 v[34:49], v[134:137], v[198:201], v[34:49]
	ds_read_b64_tr_b16 v[154:155], v244 offset:25600
	ds_read_b64_tr_b16 v[156:157], v244 offset:27648
	s_waitcnt lgkmcnt(8)
	v_mfma_f32_32x32x16_bf16 v[34:49], v[138:141], v[202:205], v[34:49]
	ds_read_b64_tr_b16 v[158:159], v244 offset:29696
	ds_read_b64_tr_b16 v[160:161], v244 offset:31744
	s_waitcnt lgkmcnt(8)
	v_mfma_f32_32x32x16_bf16 v[34:49], v[142:145], v[206:209], v[34:49]
	ds_read_b64_tr_b16 v[194:195], v244 offset:17920
	ds_read_b64_tr_b16 v[196:197], v244 offset:19968
	s_waitcnt lgkmcnt(8)
	v_mfma_f32_32x32x16_bf16 v[18:33], v[130:133], v[146:149], v[18:33]
	ds_read_b64_tr_b16 v[198:199], v244 offset:22016
	ds_read_b64_tr_b16 v[200:201], v244 offset:24064
	s_waitcnt lgkmcnt(8)
	v_mfma_f32_32x32x16_bf16 v[18:33], v[134:137], v[150:153], v[18:33]
	ds_read_b64_tr_b16 v[202:203], v244 offset:26112
	ds_read_b64_tr_b16 v[204:205], v244 offset:28160
	s_waitcnt lgkmcnt(8)
	v_mfma_f32_32x32x16_bf16 v[18:33], v[138:141], v[154:157], v[18:33]
	ds_read_b64_tr_b16 v[206:207], v244 offset:30208
	ds_read_b64_tr_b16 v[208:209], v244 offset:32256
	s_waitcnt lgkmcnt(8)
	v_mfma_f32_32x32x16_bf16 v[18:33], v[142:145], v[158:161], v[18:33]
	s_waitcnt lgkmcnt(6)
	v_mfma_f32_32x32x16_bf16 v[2:17], v[130:133], v[194:197], v[2:17]
	s_waitcnt lgkmcnt(4)
	v_mfma_f32_32x32x16_bf16 v[2:17], v[134:137], v[198:201], v[2:17]
	s_waitcnt lgkmcnt(2)
	v_mfma_f32_32x32x16_bf16 v[2:17], v[138:141], v[202:205], v[2:17]
	s_waitcnt lgkmcnt(0)
	v_mfma_f32_32x32x16_bf16 v[2:17], v[142:145], v[206:209], v[2:17]
	s_waitcnt vmcnt(0)
	s_add_u32 s22, s22, 0x180000
	s_addc_u32 s23, s23, 0
	s_add_i32 s80, s80, 2
	s_and_b64 vcc, exec, s[46:47]
	s_waitcnt vmcnt(0) lgkmcnt(0)
	s_barrier
	s_cbranch_vccnz .LBB0_439
; #define SBAR() __builtin_amdgcn_sched_barrier(0)
; template <int OFF> __device__ __forceinline__ bf16x8 k_read(int a) { bf16x8 r; asm volatile("ds_read_b128 %0, %1 offset:%2" : "=&v"(r) : "v"(a), "i"(OFF) : "memory"); return r; }
; __device__ __forceinline__ void partialSM(f32x16& p0, f32x16& p1, float& m_reg, float& mn, float& alpha) {
;   constexpr float C = SCALE * 1.4426950408889634f;
;   float pmax = p0[0];
; #pragma unroll
;   for (int r = 1; r < 16; ++r) pmax = fmaxf(pmax, p0[r]);
; #pragma unroll
;   for (int r = 0; r < 16; ++r) pmax = fmaxf(pmax, p1[r]);
;   { auto rr = __builtin_amdgcn_permlane32_swap(__float_as_uint(pmax), __float_as_uint(pmax), false, false);
;     pmax = fmaxf(__uint_as_float(rr[0]), __uint_as_float(rr[1])); }
;   if (__builtin_expect(__all(pmax - m_reg <= THR / SCALE), 1)) { mn = m_reg; alpha = 1.f; }
;   else { mn = fmaxf(m_reg, pmax); alpha = __builtin_amdgcn_exp2f((m_reg - mn) * C); m_reg = mn; }
; template <int BUFOFF, int D0> __device__ __forceinline__ void qk_step(f32x16& p0, f32x16& p1, int ka0, const bf16x8 (&qr)[8], bf16x8 (&k0)[2], bf16x8 (&k1)[2]) {
;   if constexpr (D0 + 1 < 8) { const int a_ = ka0 ^ ((D0 + 1) << 5); k0[(D0 + 1) & 1] = k_read<BUFOFF>(a_); k1[(D0 + 1) & 1] = k_read<BUFOFF + 8192>(a_); }
;   if constexpr (D0 + 1 < 8) asm volatile("s_waitcnt lgkmcnt(2)" ::: "memory"); else asm volatile("s_waitcnt lgkmcnt(0)" ::: "memory");
;   SBAR();
;   p0 = __builtin_amdgcn_mfma_f32_32x32x16_bf16(k0[D0 & 1], qr[D0], p0, 0, 0, 0);
;   p1 = __builtin_amdgcn_mfma_f32_32x32x16_bf16(k1[D0 & 1], qr[D0], p1, 0, 0, 0);
;   SBAR();
;   if constexpr (D0 + 1 < 8) qk_step<BUFOFF, (D0 + 1 < 8 ? D0 + 1 : 7)>(p0, p1, ka0, qr, k0, k1);
; }
; template <int BUFOFF> __device__ __forceinline__ void qkt_rolling(f32x16& p0, f32x16& p1, int ka0, const bf16x8 (&qr)[8]) {
;   bf16x8 k0[2], k1[2];
;   asm volatile("s_waitcnt lgkmcnt(0)" ::: "memory");
;   k0[0] = k_read<BUFOFF>(ka0); k1[0] = k_read<BUFOFF + 8192>(ka0);
;   qk_step<BUFOFF, 0>(p0, p1, ka0, qr, k0, k1);
; }
.LBB0_430:
	s_setprio 1
	v_lshl_add_u64 v[224:225], v[214:215], 0, s[22:23]
	v_lshl_add_u64 v[228:229], v[216:217], 0, s[22:23]
	s_waitcnt lgkmcnt(0)
	ds_read_b128 v[194:197], v235 offset:0
	ds_read_b128 v[198:201], v236 offset:0
	ds_read_b128 v[202:205], v238 offset:0
	ds_read_b128 v[206:209], v239 offset:0
	ds_read_b128 v[130:133], v240 offset:0
	ds_read_b128 v[134:137], v241 offset:0
	ds_read_b128 v[138:141], v242 offset:0
	ds_read_b128 v[142:145], v243 offset:0
	v_lshl_add_u64 v[232:233], v[224:225], 0, s[10:11]
	s_add_i32 m0, s62, s25
	s_nop 0
	global_load_lds_dwordx4 v[232:233], off
	v_lshl_add_u64 v[232:233], v[228:229], 0, s[10:11]
	s_add_i32 m0, s62, s66
	s_nop 0
	global_load_lds_dwordx4 v[232:233], off
	s_waitcnt lgkmcnt(7)
	s_nop 0
	v_mfma_f32_32x32x16_bf16 v[146:161], v[194:197], v[162:165], 0
	ds_read_b128 v[194:197], v235 offset:8192
	s_waitcnt lgkmcnt(7)
	v_mfma_f32_32x32x16_bf16 v[146:161], v[198:201], v[166:169], v[146:161]
	ds_read_b128 v[198:201], v236 offset:8192
	s_waitcnt lgkmcnt(7)
	v_mfma_f32_32x32x16_bf16 v[146:161], v[202:205], v[170:173], v[146:161]
	ds_read_b128 v[202:205], v238 offset:8192
	s_waitcnt lgkmcnt(7)
	v_mfma_f32_32x32x16_bf16 v[146:161], v[206:209], v[174:177], v[146:161]
	ds_read_b128 v[206:209], v239 offset:8192
	s_waitcnt lgkmcnt(7)
	v_mfma_f32_32x32x16_bf16 v[146:161], v[130:133], v[178:181], v[146:161]
	s_waitcnt lgkmcnt(6)
	v_mfma_f32_32x32x16_bf16 v[146:161], v[134:137], v[182:185], v[146:161]
	s_waitcnt lgkmcnt(5)
	v_mfma_f32_32x32x16_bf16 v[146:161], v[138:141], v[186:189], v[146:161]
	s_waitcnt lgkmcnt(4)
	v_mfma_f32_32x32x16_bf16 v[146:161], v[142:145], v[190:193], v[146:161]
	s_waitcnt lgkmcnt(3)
	v_mfma_f32_32x32x16_bf16 v[130:145], v[194:197], v[162:165], 0
	ds_read_b128 v[194:197], v240 offset:8192
	s_waitcnt lgkmcnt(3)
	v_mfma_f32_32x32x16_bf16 v[130:145], v[198:201], v[166:169], v[130:145]
	ds_read_b128 v[198:201], v241 offset:8192
	s_waitcnt lgkmcnt(3)
	v_mfma_f32_32x32x16_bf16 v[130:145], v[202:205], v[170:173], v[130:145]
	ds_read_b128 v[202:205], v242 offset:8192
	s_waitcnt lgkmcnt(3)
	v_mfma_f32_32x32x16_bf16 v[130:145], v[206:209], v[174:177], v[130:145]
	ds_read_b128 v[206:209], v243 offset:8192
	s_waitcnt lgkmcnt(3)
	v_mfma_f32_32x32x16_bf16 v[130:145], v[194:197], v[178:181], v[130:145]
	s_waitcnt lgkmcnt(2)
	v_mfma_f32_32x32x16_bf16 v[130:145], v[198:201], v[182:185], v[130:145]
	s_waitcnt lgkmcnt(1)
	v_mfma_f32_32x32x16_bf16 v[130:145], v[202:205], v[186:189], v[130:145]
	s_waitcnt lgkmcnt(0)
	v_mfma_f32_32x32x16_bf16 v[130:145], v[206:209], v[190:193], v[130:145]
	s_setprio 0
	v_max3_f32 v0, v146, v147, v148
	v_max3_f32 v194, v154, v155, v156
	v_max3_f32 v0, v0, v149, v150
	v_max3_f32 v194, v194, v157, v158
	v_max3_f32 v0, v0, v151, v152
	v_max3_f32 v194, v194, v159, v160
	v_max_f32_e32 v0, v0, v153
	v_max_f32_e32 v194, v194, v161
	s_nop 4
	v_max3_f32 v196, v130, v131, v132
	v_max3_f32 v197, v138, v139, v140
	v_max3_f32 v196, v196, v133, v134
	v_max3_f32 v197, v197, v141, v142
	v_max3_f32 v196, v196, v135, v136
	v_max3_f32 v197, v197, v143, v144
	v_max_f32_e32 v196, v196, v137
	v_max_f32_e32 v197, v197, v145
	v_max3_f32 v0, v0, v194, v196
	v_max_f32_e32 v0, v0, v197
	v_mov_b32_e32 v194, v0
	s_nop 1
	v_permlane32_swap_b32_e32 v0, v194
	v_max_f32_e32 v0, v0, v194
	v_sub_f32_e32 v194, v0, v246
	v_cmp_ge_f32_e32 vcc, s63, v194
	s_cmp_eq_u64 vcc, exec
	s_cbranch_scc0 .Lda_slow_l0_3
	s_mov_b64 s[6:7], -1
	v_mov_b32_e32 v0, 1.0
	s_branch .LBB0_434
.Lda_slow_l0_3:
	v_max_f32_e32 v247, v246, v0
	v_sub_f32_e32 v0, v246, v247
	v_mul_f32_e32 v0, 0x3e0293ee, v0
	v_exp_f32_e32 v0, v0
	s_mov_b64 s[6:7], 0
	s_nop 0
	v_cmp_gt_f32_e32 vcc, 1.0, v0
	s_cbranch_vccz .LBB0_434
	s_and_saveexec_b64 s[46:47], s[4:5]
	ds_write_b32 v237, v0 offset:128
	s_or_b64 exec, exec, s[46:47]
	s_waitcnt lgkmcnt(0)
	v_add_u32_e32 v194, s24, v212
	ds_read_b128 v[206:209], v194 offset:224
	ds_read_b128 v[202:205], v194 offset:192
	ds_read_b128 v[198:201], v194 offset:160
	ds_read_b128 v[194:197], v194 offset:128
	s_waitcnt lgkmcnt(0)
	v_pk_mul_f32 v[126:127], v[126:127], v[206:207]
	v_pk_mul_f32 v[122:123], v[122:123], v[202:203]
	v_pk_mul_f32 v[118:119], v[118:119], v[198:199]
	v_pk_mul_f32 v[128:129], v[128:129], v[208:209]
	v_pk_mul_f32 v[124:125], v[124:125], v[204:205]
	v_pk_mul_f32 v[120:121], v[120:121], v[200:201]
	v_pk_mul_f32 v[116:117], v[116:117], v[196:197]
	v_pk_mul_f32 v[114:115], v[114:115], v[194:195]
	v_pk_mul_f32 v[110:111], v[110:111], v[206:207]
	v_pk_mul_f32 v[106:107], v[106:107], v[202:203]
	v_pk_mul_f32 v[102:103], v[102:103], v[198:199]
	v_pk_mul_f32 v[112:113], v[112:113], v[208:209]
	v_pk_mul_f32 v[108:109], v[108:109], v[204:205]
	v_pk_mul_f32 v[104:105], v[104:105], v[200:201]
	v_pk_mul_f32 v[100:101], v[100:101], v[196:197]
	v_pk_mul_f32 v[98:99], v[98:99], v[194:195]
	v_pk_mul_f32 v[94:95], v[94:95], v[206:207]
	v_pk_mul_f32 v[90:91], v[90:91], v[202:203]
	v_pk_mul_f32 v[86:87], v[86:87], v[198:199]
	v_pk_mul_f32 v[96:97], v[96:97], v[208:209]
	v_pk_mul_f32 v[92:93], v[92:93], v[204:205]
	v_pk_mul_f32 v[88:89], v[88:89], v[200:201]
	v_pk_mul_f32 v[84:85], v[84:85], v[196:197]
	v_pk_mul_f32 v[82:83], v[82:83], v[194:195]
	v_pk_mul_f32 v[78:79], v[78:79], v[206:207]
	v_pk_mul_f32 v[74:75], v[74:75], v[202:203]
	v_pk_mul_f32 v[70:71], v[70:71], v[198:199]
	v_pk_mul_f32 v[80:81], v[80:81], v[208:209]
	v_pk_mul_f32 v[76:77], v[76:77], v[204:205]
	v_pk_mul_f32 v[72:73], v[72:73], v[200:201]
	v_pk_mul_f32 v[68:69], v[68:69], v[196:197]
	v_pk_mul_f32 v[66:67], v[66:67], v[194:195]
	v_pk_mul_f32 v[62:63], v[62:63], v[206:207]
	v_pk_mul_f32 v[58:59], v[58:59], v[202:203]
	v_pk_mul_f32 v[54:55], v[54:55], v[198:199]
	v_pk_mul_f32 v[64:65], v[64:65], v[208:209]
	v_pk_mul_f32 v[60:61], v[60:61], v[204:205]
	v_pk_mul_f32 v[56:57], v[56:57], v[200:201]
	v_pk_mul_f32 v[52:53], v[52:53], v[196:197]
	v_pk_mul_f32 v[50:51], v[50:51], v[194:195]
	v_pk_mul_f32 v[46:47], v[46:47], v[206:207]
	v_pk_mul_f32 v[42:43], v[42:43], v[202:203]
	v_pk_mul_f32 v[38:39], v[38:39], v[198:199]
	v_pk_mul_f32 v[48:49], v[48:49], v[208:209]
	v_pk_mul_f32 v[44:45], v[44:45], v[204:205]
	v_pk_mul_f32 v[40:41], v[40:41], v[200:201]
	v_pk_mul_f32 v[36:37], v[36:37], v[196:197]
	v_pk_mul_f32 v[34:35], v[34:35], v[194:195]
	v_pk_mul_f32 v[30:31], v[30:31], v[206:207]
	v_pk_mul_f32 v[26:27], v[26:27], v[202:203]
	v_pk_mul_f32 v[22:23], v[22:23], v[198:199]
	v_pk_mul_f32 v[32:33], v[32:33], v[208:209]
	v_pk_mul_f32 v[28:29], v[28:29], v[204:205]
	v_pk_mul_f32 v[24:25], v[24:25], v[200:201]
	v_pk_mul_f32 v[20:21], v[20:21], v[196:197]
	v_pk_mul_f32 v[18:19], v[18:19], v[194:195]
	v_pk_mul_f32 v[14:15], v[14:15], v[206:207]
	v_pk_mul_f32 v[10:11], v[10:11], v[202:203]
	v_pk_mul_f32 v[6:7], v[6:7], v[198:199]
	v_pk_mul_f32 v[16:17], v[16:17], v[208:209]
	v_pk_mul_f32 v[12:13], v[12:13], v[204:205]
	v_pk_mul_f32 v[8:9], v[8:9], v[200:201]
	v_pk_mul_f32 v[4:5], v[4:5], v[196:197]
	v_pk_mul_f32 v[2:3], v[2:3], v[194:195]
; #define SBAR() __builtin_amdgcn_sched_barrier(0)
; __device__ __forceinline__ void partialSM(f32x16& p0, f32x16& p1, float& m_reg, float& mn, float& alpha) {
;     ...
;   float mnC = -mn * C;
; #pragma unroll
;   for (int r = 0; r < 16; ++r) p0[r] = fmaf(p0[r], C, mnC);
; #pragma unroll
;   for (int r = 0; r < 16; ++r) p1[r] = fmaf(p1[r], C, mnC);
; #pragma unroll
;   for (int r = 0; r < 16; ++r) p0[r] = __builtin_amdgcn_exp2f(p0[r]);
; }
; __device__ __forceinline__ void finishSM(f32x16& p0, f32x16& p1, float alpha, float& l_reg, bf16x8& pa0, bf16x8& pa1, bf16x8& pa2, bf16x8& pa3) {
; #pragma unroll
;   for (int r = 0; r < 16; ++r) p1[r] = __builtin_amdgcn_exp2f(p1[r]);
;   float ps = 0;
; #pragma unroll
;   for (int r = 0; r < 16; ++r) ps += p0[r];
; #pragma unroll
;   for (int r = 0; r < 16; ++r) ps += p1[r];
;   { auto rr = __builtin_amdgcn_permlane32_swap(__float_as_uint(ps), __float_as_uint(ps), false, false);
;     ps = __uint_as_float(rr[0]) + __uint_as_float(rr[1]); }
;   l_reg = l_reg * alpha + ps;
;     ...
;   PK4(p0, 0, pa0); PK4(p0, 8, pa1); PK4(p1, 0, pa2); PK4(p1, 8, pa3);
;     ...
; }
; template <int I> __device__ __forceinline__ void pv_step(f32x16* o, int vb, const bf16x8 (&pa)[4], s16x4 (&l)[3], s16x4 (&h)[3]) {
;   if constexpr (I + 2 < 32) pv_rd<(I + 2 < 32 ? I + 2 : 0)>(vb, l[(I + 2) % 3], h[(I + 2) % 3]);
;   if constexpr (I + 2 < 32) asm volatile("s_waitcnt lgkmcnt(4)" ::: "memory"); else if constexpr (I + 1 < 32) asm volatile("s_waitcnt lgkmcnt(2)" ::: "memory"); else asm volatile("s_waitcnt lgkmcnt(0)" ::: "memory");
;   SBAR();
;   const s16x4 L = l[I % 3], H = h[I % 3];
;   o[I >> 2] = __builtin_amdgcn_mfma_f32_32x32x16_bf16(pa[I & 3], (bf16x8){L[0], L[1], L[2], L[3], H[0], H[1], H[2], H[3]}, o[I >> 2], 0, 0, 0);
;   SBAR();
;   if constexpr (I + 1 < 32) pv_step<(I + 1 < 32 ? I + 1 : 31)>(o, vb, pa, l, h);
; }
; __device__ __forceinline__ void pv_all_rolling(f32x16* o, int vb, bf16x8 pa0, bf16x8 pa1, bf16x8 pa2, bf16x8 pa3) {
;   const bf16x8 pa[4] = {pa0, pa1, pa2, pa3}; s16x4 l[3], h[3];
;   asm volatile("s_waitcnt lgkmcnt(0)" ::: "memory");
;   pv_rd<0>(vb, l[0], h[0]); pv_rd<1>(vb, l[1], h[1]);
;   pv_step<0>(o, vb, pa, l, h);
.LBB0_434:
	v_cndmask_b32_e64 v246, v247, v246, s[6:7]
	v_mul_f32_e32 v194, 0xbe0293ee, v246
	v_fmamk_f32 v146, v146, 0x3e0293ee, v194
	v_fmamk_f32 v147, v147, 0x3e0293ee, v194
	v_fmamk_f32 v148, v148, 0x3e0293ee, v194
	v_fmamk_f32 v149, v149, 0x3e0293ee, v194
	v_fmamk_f32 v150, v150, 0x3e0293ee, v194
	v_fmamk_f32 v151, v151, 0x3e0293ee, v194
	v_fmamk_f32 v152, v152, 0x3e0293ee, v194
	v_fmamk_f32 v153, v153, 0x3e0293ee, v194
	v_fmamk_f32 v154, v154, 0x3e0293ee, v194
	v_fmamk_f32 v155, v155, 0x3e0293ee, v194
	v_fmamk_f32 v156, v156, 0x3e0293ee, v194
	v_fmamk_f32 v157, v157, 0x3e0293ee, v194
	v_fmamk_f32 v158, v158, 0x3e0293ee, v194
	v_fmamk_f32 v159, v159, 0x3e0293ee, v194
	v_fmamk_f32 v160, v160, 0x3e0293ee, v194
	v_fmamk_f32 v161, v161, 0x3e0293ee, v194
	v_fmamk_f32 v130, v130, 0x3e0293ee, v194
	v_fmamk_f32 v131, v131, 0x3e0293ee, v194
	v_fmamk_f32 v132, v132, 0x3e0293ee, v194
	v_fmamk_f32 v133, v133, 0x3e0293ee, v194
	v_fmamk_f32 v134, v134, 0x3e0293ee, v194
	v_fmamk_f32 v135, v135, 0x3e0293ee, v194
	v_fmamk_f32 v136, v136, 0x3e0293ee, v194
	v_fmamk_f32 v137, v137, 0x3e0293ee, v194
	v_fmamk_f32 v138, v138, 0x3e0293ee, v194
	v_fmamk_f32 v139, v139, 0x3e0293ee, v194
	v_fmamk_f32 v140, v140, 0x3e0293ee, v194
	v_fmamk_f32 v141, v141, 0x3e0293ee, v194
	v_fmamk_f32 v142, v142, 0x3e0293ee, v194
	v_fmamk_f32 v143, v143, 0x3e0293ee, v194
	v_fmamk_f32 v144, v144, 0x3e0293ee, v194
	v_fmac_f32_e32 v194, 0x3e0293ee, v145
	v_exp_f32_e32 v145, v146
	v_exp_f32_e32 v146, v147
	v_exp_f32_e32 v147, v148
	v_exp_f32_e32 v148, v149
	v_exp_f32_e32 v149, v150
	v_exp_f32_e32 v150, v151
	v_exp_f32_e32 v151, v152
	v_exp_f32_e32 v152, v153
	v_exp_f32_e32 v153, v154
	v_exp_f32_e32 v154, v155
	v_exp_f32_e32 v155, v156
	v_exp_f32_e32 v156, v157
	v_exp_f32_e32 v157, v158
	v_exp_f32_e32 v158, v159
	v_exp_f32_e32 v159, v160
	v_exp_f32_e32 v160, v161
	v_exp_f32_e32 v161, v130
	v_add_f32_e32 v130, 0, v145
	v_add_f32_e32 v130, v146, v130
	v_add_f32_e32 v130, v147, v130
	v_add_f32_e32 v130, v148, v130
	v_add_f32_e32 v130, v149, v130
	v_add_f32_e32 v130, v150, v130
	v_add_f32_e32 v130, v151, v130
	s_waitcnt vmcnt(0)
	s_barrier
	s_setprio 0
	v_add_f32_e32 v130, v152, v130
	v_add_f32_e32 v130, v153, v130
	v_add_f32_e32 v130, v154, v130
	v_add_f32_e32 v130, v155, v130
	v_add_f32_e32 v130, v156, v130
	v_add_f32_e32 v130, v157, v130
	v_exp_f32_e32 v195, v131
	v_add_f32_e32 v130, v158, v130
	v_exp_f32_e32 v196, v132
	v_add_f32_e32 v130, v159, v130
	v_exp_f32_e32 v197, v133
	v_add_f32_e32 v130, v160, v130
	v_exp_f32_e32 v198, v134
	v_add_f32_e32 v130, v161, v130
	v_exp_f32_e32 v199, v135
	v_add_f32_e32 v130, v195, v130
	v_exp_f32_e32 v200, v136
	v_add_f32_e32 v130, v196, v130
	v_exp_f32_e32 v201, v137
	v_add_f32_e32 v130, v197, v130
	v_exp_f32_e32 v202, v138
	v_add_f32_e32 v130, v198, v130
	v_exp_f32_e32 v203, v139
	v_add_f32_e32 v130, v199, v130
	v_exp_f32_e32 v204, v140
	v_add_f32_e32 v130, v200, v130
	v_exp_f32_e32 v205, v141
	v_add_f32_e32 v130, v201, v130
	v_exp_f32_e32 v206, v142
	v_add_f32_e32 v130, v202, v130
	v_exp_f32_e32 v207, v143
	v_add_f32_e32 v130, v203, v130
	v_exp_f32_e32 v208, v144
	v_add_f32_e32 v130, v204, v130
	v_exp_f32_e32 v194, v194
	v_add_f32_e32 v130, v205, v130
	v_add_f32_e32 v130, v206, v130
	v_add_f32_e32 v130, v207, v130
	v_add_f32_e32 v130, v208, v130
	v_add_f32_e32 v247, v194, v130
	v_mov_b32_e32 v248, v247
	s_nop 1
	v_permlane32_swap_b32_e32 v247, v248
	v_cvt_pk_bf16_f32 v130, v145, v146
	v_cvt_pk_bf16_f32 v131, v147, v148
	v_cvt_pk_bf16_f32 v132, v149, v150
	v_cvt_pk_bf16_f32 v133, v151, v152
	v_cvt_pk_bf16_f32 v134, v153, v154
	v_cvt_pk_bf16_f32 v135, v155, v156
	v_cvt_pk_bf16_f32 v136, v157, v158
	v_cvt_pk_bf16_f32 v137, v159, v160
	v_cvt_pk_bf16_f32 v138, v161, v195
	v_cvt_pk_bf16_f32 v139, v196, v197
	v_cvt_pk_bf16_f32 v140, v198, v199
	v_cvt_pk_bf16_f32 v141, v200, v201
	v_cvt_pk_bf16_f32 v142, v202, v203
	v_cvt_pk_bf16_f32 v143, v204, v205
	v_cvt_pk_bf16_f32 v144, v206, v207
	v_cvt_pk_bf16_f32 v145, v208, v194
	s_nop 0
	v_permlane32_swap_b32_e32 v130, v132
	v_permlane32_swap_b32_e32 v131, v133
	v_permlane32_swap_b32_e32 v134, v136
	v_permlane32_swap_b32_e32 v135, v137
	v_permlane32_swap_b32_e32 v138, v140
	v_permlane32_swap_b32_e32 v139, v141
	v_permlane32_swap_b32_e32 v142, v144
	v_permlane32_swap_b32_e32 v143, v145
	s_waitcnt lgkmcnt(0)
	ds_read_b64_tr_b16 v[146:147], v213 offset:0
	ds_read_b64_tr_b16 v[148:149], v213 offset:2048
	ds_read_b64_tr_b16 v[150:151], v213 offset:4096
	ds_read_b64_tr_b16 v[152:153], v213 offset:6144
	ds_read_b64_tr_b16 v[154:155], v213 offset:8192
	ds_read_b64_tr_b16 v[156:157], v213 offset:10240
	ds_read_b64_tr_b16 v[158:159], v213 offset:12288
	ds_read_b64_tr_b16 v[160:161], v213 offset:14336
	ds_read_b64_tr_b16 v[194:195], v213 offset:512
	ds_read_b64_tr_b16 v[196:197], v213 offset:2560
	v_lshl_add_u64 v[232:233], v[218:219], 0, s[22:23]
	v_lshl_add_u64 v[232:233], v[232:233], 0, s[10:11]
	s_add_i32 m0, s29, 0x8000
	s_nop 0
	global_load_lds_dwordx4 v[232:233], off
	s_waitcnt lgkmcnt(8)
	s_nop 0
	v_mfma_f32_32x32x16_bf16 v[114:129], v[130:133], v[146:149], v[114:129]
	ds_read_b64_tr_b16 v[198:199], v213 offset:4608
	ds_read_b64_tr_b16 v[200:201], v213 offset:6656
	v_lshl_add_u64 v[232:233], v[218:219], 0, s[22:23]
	v_lshl_add_u64 v[232:233], v[232:233], 0, s[12:13]
	s_add_i32 m0, s29, 0xc000
	s_nop 0
	global_load_lds_dwordx4 v[232:233], off
	s_waitcnt lgkmcnt(8)
	v_mfma_f32_32x32x16_bf16 v[114:129], v[134:137], v[150:153], v[114:129]
	ds_read_b64_tr_b16 v[202:203], v213 offset:8704
	ds_read_b64_tr_b16 v[204:205], v213 offset:10752
	v_lshl_add_u64 v[232:233], v[220:221], 0, s[22:23]
	v_lshl_add_u64 v[232:233], v[232:233], 0, s[10:11]
	s_add_i32 m0, s29, 0x8400
	s_nop 0
	global_load_lds_dwordx4 v[232:233], off
	s_waitcnt lgkmcnt(8)
; #define SBAR() __builtin_amdgcn_sched_barrier(0)
; #define DPUB() do { asm volatile("s_waitcnt vmcnt(0)" ::: "memory"); __syncthreads(); } while (0)
; #define DTILE(b) do { f32x16 p0 = f32x16{}, p1 = f32x16{}; float mn, al; bf16x8 pa0, pa1, pa2, pa3; \
;     qkt_rolling<(b) * DA_KB>(p0, p1, ka0, qr); partialSM(p0, p1, m_reg, mn, al); DRESC(al); finishSM(p0, p1, al, l_reg, pa0, pa1, pa2, pa3); SBAR(); \
;     pv_all_rolling(o, vb0 + (b) * DA_VB, pa0, pa1, pa2, pa3); } while (0)
; template <int I> __device__ __forceinline__ void pv_step(f32x16* o, int vb, const bf16x8 (&pa)[4], s16x4 (&l)[3], s16x4 (&h)[3]) {
;   if constexpr (I + 2 < 32) pv_rd<(I + 2 < 32 ? I + 2 : 0)>(vb, l[(I + 2) % 3], h[(I + 2) % 3]);
;   if constexpr (I + 2 < 32) asm volatile("s_waitcnt lgkmcnt(4)" ::: "memory"); else if constexpr (I + 1 < 32) asm volatile("s_waitcnt lgkmcnt(2)" ::: "memory"); else asm volatile("s_waitcnt lgkmcnt(0)" ::: "memory");
;   SBAR();
;   const s16x4 L = l[I % 3], H = h[I % 3];
;   o[I >> 2] = __builtin_amdgcn_mfma_f32_32x32x16_bf16(pa[I & 3], (bf16x8){L[0], L[1], L[2], L[3], H[0], H[1], H[2], H[3]}, o[I >> 2], 0, 0, 0);
;   SBAR();
;   if constexpr (I + 1 < 32) pv_step<(I + 1 < 32 ? I + 1 : 31)>(o, vb, pa, l, h);
; }
; __device__ __forceinline__ void pv_all_rolling(f32x16* o, int vb, bf16x8 pa0, bf16x8 pa1, bf16x8 pa2, bf16x8 pa3) {
;   const bf16x8 pa[4] = {pa0, pa1, pa2, pa3}; s16x4 l[3], h[3];
;   asm volatile("s_waitcnt lgkmcnt(0)" ::: "memory");
;   pv_rd<0>(vb, l[0], h[0]); pv_rd<1>(vb, l[1], h[1]);
;   pv_step<0>(o, vb, pa, l, h);
; __device__ __forceinline__ void unit_body_da(const Unit& U, char* lds) {
;     ...
;   for (int j = 0; j < NT; j += 2) {
;     DDMA(j + 1, 1); SBAR();
;     DTILE(0); SBAR(); DPUB();
;     if (j + 2 < NT) DDMA(j + 2, 0); SBAR();
;     DTILE(1); SBAR(); DPUB();
;   }
	v_mfma_f32_32x32x16_bf16 v[114:129], v[138:141], v[154:157], v[114:129]
	ds_read_b64_tr_b16 v[206:207], v213 offset:12800
	ds_read_b64_tr_b16 v[208:209], v213 offset:14848
	v_lshl_add_u64 v[232:233], v[220:221], 0, s[22:23]
	v_lshl_add_u64 v[232:233], v[232:233], 0, s[12:13]
	s_add_i32 m0, s29, 0xc400
	s_nop 0
	global_load_lds_dwordx4 v[232:233], off
	s_waitcnt lgkmcnt(8)
	v_mfma_f32_32x32x16_bf16 v[114:129], v[142:145], v[158:161], v[114:129]
	ds_read_b64_tr_b16 v[146:147], v213 offset:1024
	ds_read_b64_tr_b16 v[148:149], v213 offset:3072
	s_waitcnt lgkmcnt(8)
	v_mfma_f32_32x32x16_bf16 v[98:113], v[130:133], v[194:197], v[98:113]
	ds_read_b64_tr_b16 v[150:151], v213 offset:5120
	ds_read_b64_tr_b16 v[152:153], v213 offset:7168
	s_waitcnt lgkmcnt(8)
	v_mfma_f32_32x32x16_bf16 v[98:113], v[134:137], v[198:201], v[98:113]
	ds_read_b64_tr_b16 v[154:155], v213 offset:9216
	ds_read_b64_tr_b16 v[156:157], v213 offset:11264
	s_waitcnt lgkmcnt(8)
	v_mfma_f32_32x32x16_bf16 v[98:113], v[138:141], v[202:205], v[98:113]
	ds_read_b64_tr_b16 v[158:159], v213 offset:13312
	ds_read_b64_tr_b16 v[160:161], v213 offset:15360
	s_waitcnt lgkmcnt(8)
	v_mfma_f32_32x32x16_bf16 v[98:113], v[142:145], v[206:209], v[98:113]
	ds_read_b64_tr_b16 v[194:195], v213 offset:1536
	ds_read_b64_tr_b16 v[196:197], v213 offset:3584
	s_waitcnt lgkmcnt(8)
	v_mfma_f32_32x32x16_bf16 v[82:97], v[130:133], v[146:149], v[82:97]
	ds_read_b64_tr_b16 v[198:199], v213 offset:5632
	ds_read_b64_tr_b16 v[200:201], v213 offset:7680
	s_waitcnt lgkmcnt(8)
	v_mfma_f32_32x32x16_bf16 v[82:97], v[134:137], v[150:153], v[82:97]
	ds_read_b64_tr_b16 v[202:203], v213 offset:9728
	ds_read_b64_tr_b16 v[204:205], v213 offset:11776
	s_waitcnt lgkmcnt(8)
	v_mfma_f32_32x32x16_bf16 v[82:97], v[138:141], v[154:157], v[82:97]
	ds_read_b64_tr_b16 v[206:207], v213 offset:13824
	ds_read_b64_tr_b16 v[208:209], v213 offset:15872
	s_waitcnt lgkmcnt(8)
	v_mfma_f32_32x32x16_bf16 v[82:97], v[142:145], v[158:161], v[82:97]
	ds_read_b64_tr_b16 v[146:147], v213 offset:16384
	ds_read_b64_tr_b16 v[148:149], v213 offset:18432
	s_waitcnt lgkmcnt(8)
	v_mfma_f32_32x32x16_bf16 v[66:81], v[130:133], v[194:197], v[66:81]
	ds_read_b64_tr_b16 v[150:151], v213 offset:20480
	ds_read_b64_tr_b16 v[152:153], v213 offset:22528
	s_waitcnt lgkmcnt(8)
	v_mfma_f32_32x32x16_bf16 v[66:81], v[134:137], v[198:201], v[66:81]
	ds_read_b64_tr_b16 v[154:155], v213 offset:24576
	ds_read_b64_tr_b16 v[156:157], v213 offset:26624
	s_waitcnt lgkmcnt(8)
	v_mfma_f32_32x32x16_bf16 v[66:81], v[138:141], v[202:205], v[66:81]
	ds_read_b64_tr_b16 v[158:159], v213 offset:28672
	ds_read_b64_tr_b16 v[160:161], v213 offset:30720
	s_waitcnt lgkmcnt(8)
	v_mfma_f32_32x32x16_bf16 v[66:81], v[142:145], v[206:209], v[66:81]
	ds_read_b64_tr_b16 v[194:195], v213 offset:16896
	ds_read_b64_tr_b16 v[196:197], v213 offset:18944
	s_waitcnt lgkmcnt(8)
	v_mfma_f32_32x32x16_bf16 v[50:65], v[130:133], v[146:149], v[50:65]
	ds_read_b64_tr_b16 v[198:199], v213 offset:20992
	ds_read_b64_tr_b16 v[200:201], v213 offset:23040
	s_waitcnt lgkmcnt(8)
	v_mfma_f32_32x32x16_bf16 v[50:65], v[134:137], v[150:153], v[50:65]
	ds_read_b64_tr_b16 v[202:203], v213 offset:25088
	ds_read_b64_tr_b16 v[204:205], v213 offset:27136
	s_waitcnt lgkmcnt(8)
	v_mfma_f32_32x32x16_bf16 v[50:65], v[138:141], v[154:157], v[50:65]
	ds_read_b64_tr_b16 v[206:207], v213 offset:29184
	ds_read_b64_tr_b16 v[208:209], v213 offset:31232
	s_waitcnt lgkmcnt(8)
	v_mfma_f32_32x32x16_bf16 v[50:65], v[142:145], v[158:161], v[50:65]
	ds_read_b64_tr_b16 v[146:147], v213 offset:17408
	ds_read_b64_tr_b16 v[148:149], v213 offset:19456
	s_waitcnt lgkmcnt(8)
	v_mfma_f32_32x32x16_bf16 v[34:49], v[130:133], v[194:197], v[34:49]
	ds_read_b64_tr_b16 v[150:151], v213 offset:21504
	ds_read_b64_tr_b16 v[152:153], v213 offset:23552
	s_waitcnt lgkmcnt(8)
	v_mfma_f32_32x32x16_bf16 v[34:49], v[134:137], v[198:201], v[34:49]
	ds_read_b64_tr_b16 v[154:155], v213 offset:25600
	ds_read_b64_tr_b16 v[156:157], v213 offset:27648
	s_waitcnt lgkmcnt(8)
	v_mfma_f32_32x32x16_bf16 v[34:49], v[138:141], v[202:205], v[34:49]
	ds_read_b64_tr_b16 v[158:159], v213 offset:29696
	ds_read_b64_tr_b16 v[160:161], v213 offset:31744
	s_waitcnt lgkmcnt(8)
	v_mfma_f32_32x32x16_bf16 v[34:49], v[142:145], v[206:209], v[34:49]
	ds_read_b64_tr_b16 v[194:195], v213 offset:17920
	ds_read_b64_tr_b16 v[196:197], v213 offset:19968
	s_waitcnt lgkmcnt(8)
	v_mfma_f32_32x32x16_bf16 v[18:33], v[130:133], v[146:149], v[18:33]
	ds_read_b64_tr_b16 v[198:199], v213 offset:22016
	ds_read_b64_tr_b16 v[200:201], v213 offset:24064
	s_waitcnt lgkmcnt(8)
	v_mfma_f32_32x32x16_bf16 v[18:33], v[134:137], v[150:153], v[18:33]
	ds_read_b64_tr_b16 v[202:203], v213 offset:26112
	ds_read_b64_tr_b16 v[204:205], v213 offset:28160
	s_waitcnt lgkmcnt(8)
	v_mfma_f32_32x32x16_bf16 v[18:33], v[138:141], v[154:157], v[18:33]
	ds_read_b64_tr_b16 v[206:207], v213 offset:30208
	ds_read_b64_tr_b16 v[208:209], v213 offset:32256
	s_waitcnt lgkmcnt(8)
	v_mfma_f32_32x32x16_bf16 v[18:33], v[142:145], v[158:161], v[18:33]
	s_waitcnt lgkmcnt(6)
	v_mfma_f32_32x32x16_bf16 v[2:17], v[130:133], v[194:197], v[2:17]
	s_waitcnt lgkmcnt(4)
	v_mfma_f32_32x32x16_bf16 v[2:17], v[134:137], v[198:201], v[2:17]
	s_waitcnt lgkmcnt(2)
	v_mfma_f32_32x32x16_bf16 v[2:17], v[138:141], v[202:205], v[2:17]
	s_waitcnt lgkmcnt(0)
	v_mfma_f32_32x32x16_bf16 v[2:17], v[142:145], v[206:209], v[2:17]
	s_waitcnt vmcnt(0)
	s_cmp_ge_u32 s80, s0
	s_cselect_b64 s[46:47], -1, 0
	s_and_b64 vcc, exec, s[46:47]
	s_waitcnt vmcnt(0) lgkmcnt(0)
	s_barrier
; #define SBAR() __builtin_amdgcn_sched_barrier(0)
; template <int OFF> __device__ __forceinline__ bf16x8 k_read(int a) { bf16x8 r; asm volatile("ds_read_b128 %0, %1 offset:%2" : "=&v"(r) : "v"(a), "i"(OFF) : "memory"); return r; }
; __device__ __forceinline__ void partialSM(f32x16& p0, f32x16& p1, float& m_reg, float& mn, float& alpha) {
;   constexpr float C = SCALE * 1.4426950408889634f;
;   float pmax = p0[0];
; #pragma unroll
;   for (int r = 1; r < 16; ++r) pmax = fmaxf(pmax, p0[r]);
; #pragma unroll
;   for (int r = 0; r < 16; ++r) pmax = fmaxf(pmax, p1[r]);
;   { auto rr = __builtin_amdgcn_permlane32_swap(__float_as_uint(pmax), __float_as_uint(pmax), false, false);
;     pmax = fmaxf(__uint_as_float(rr[0]), __uint_as_float(rr[1])); }
;   if (__builtin_expect(__all(pmax - m_reg <= THR / SCALE), 1)) { mn = m_reg; alpha = 1.f; }
;   else { mn = fmaxf(m_reg, pmax); alpha = __builtin_amdgcn_exp2f((m_reg - mn) * C); m_reg = mn; }
; template <int BUFOFF, int D0> __device__ __forceinline__ void qk_step(f32x16& p0, f32x16& p1, int ka0, const bf16x8 (&qr)[8], bf16x8 (&k0)[2], bf16x8 (&k1)[2]) {
;   if constexpr (D0 + 1 < 8) { const int a_ = ka0 ^ ((D0 + 1) << 5); k0[(D0 + 1) & 1] = k_read<BUFOFF>(a_); k1[(D0 + 1) & 1] = k_read<BUFOFF + 8192>(a_); }
;   if constexpr (D0 + 1 < 8) asm volatile("s_waitcnt lgkmcnt(2)" ::: "memory"); else asm volatile("s_waitcnt lgkmcnt(0)" ::: "memory");
;   SBAR();
;   p0 = __builtin_amdgcn_mfma_f32_32x32x16_bf16(k0[D0 & 1], qr[D0], p0, 0, 0, 0);
;   p1 = __builtin_amdgcn_mfma_f32_32x32x16_bf16(k1[D0 & 1], qr[D0], p1, 0, 0, 0);
;   SBAR();
;   if constexpr (D0 + 1 < 8) qk_step<BUFOFF, (D0 + 1 < 8 ? D0 + 1 : 7)>(p0, p1, ka0, qr, k0, k1);
; }
; template <int BUFOFF> __device__ __forceinline__ void qkt_rolling(f32x16& p0, f32x16& p1, int ka0, const bf16x8 (&qr)[8]) {
;   bf16x8 k0[2], k1[2];
;   asm volatile("s_waitcnt lgkmcnt(0)" ::: "memory");
;   k0[0] = k_read<BUFOFF>(ka0); k1[0] = k_read<BUFOFF + 8192>(ka0);
;   qk_step<BUFOFF, 0>(p0, p1, ka0, qr, k0, k1);
; }
.LBB0_436:
	s_setprio 1
	s_waitcnt lgkmcnt(0)
	ds_read_b128 v[194:197], v235 offset:16384
	ds_read_b128 v[198:201], v236 offset:16384
	ds_read_b128 v[202:205], v238 offset:16384
	ds_read_b128 v[206:209], v239 offset:16384
	ds_read_b128 v[130:133], v240 offset:16384
	ds_read_b128 v[134:137], v241 offset:16384
	ds_read_b128 v[138:141], v242 offset:16384
	ds_read_b128 v[142:145], v243 offset:16384
	v_lshl_add_u64 v[232:233], v[224:225], 0, s[14:15]
	s_mov_b32 m0, s28
	s_nop 0
	global_load_lds_dwordx4 v[232:233], off
	v_lshl_add_u64 v[232:233], v[228:229], 0, s[14:15]
	s_mov_b32 m0, s67
	s_nop 0
	global_load_lds_dwordx4 v[232:233], off
	s_waitcnt lgkmcnt(7)
	s_nop 0
	v_mfma_f32_32x32x16_bf16 v[146:161], v[194:197], v[162:165], 0
	ds_read_b128 v[194:197], v235 offset:24576
	s_waitcnt lgkmcnt(7)
	v_mfma_f32_32x32x16_bf16 v[146:161], v[198:201], v[166:169], v[146:161]
	ds_read_b128 v[198:201], v236 offset:24576
	s_waitcnt lgkmcnt(7)
	v_mfma_f32_32x32x16_bf16 v[146:161], v[202:205], v[170:173], v[146:161]
	ds_read_b128 v[202:205], v238 offset:24576
	s_waitcnt lgkmcnt(7)
	v_mfma_f32_32x32x16_bf16 v[146:161], v[206:209], v[174:177], v[146:161]
	ds_read_b128 v[206:209], v239 offset:24576
	s_waitcnt lgkmcnt(7)
	v_mfma_f32_32x32x16_bf16 v[146:161], v[130:133], v[178:181], v[146:161]
	s_waitcnt lgkmcnt(6)
	v_mfma_f32_32x32x16_bf16 v[146:161], v[134:137], v[182:185], v[146:161]
	s_waitcnt lgkmcnt(5)
	v_mfma_f32_32x32x16_bf16 v[146:161], v[138:141], v[186:189], v[146:161]
	s_waitcnt lgkmcnt(4)
	v_mfma_f32_32x32x16_bf16 v[146:161], v[142:145], v[190:193], v[146:161]
	s_waitcnt lgkmcnt(3)
	v_mfma_f32_32x32x16_bf16 v[130:145], v[194:197], v[162:165], 0
	ds_read_b128 v[194:197], v240 offset:24576
	s_waitcnt lgkmcnt(3)
	v_mfma_f32_32x32x16_bf16 v[130:145], v[198:201], v[166:169], v[130:145]
	ds_read_b128 v[198:201], v241 offset:24576
	s_waitcnt lgkmcnt(3)
	v_mfma_f32_32x32x16_bf16 v[130:145], v[202:205], v[170:173], v[130:145]
	ds_read_b128 v[202:205], v242 offset:24576
	s_waitcnt lgkmcnt(3)
	v_mfma_f32_32x32x16_bf16 v[130:145], v[206:209], v[174:177], v[130:145]
	ds_read_b128 v[206:209], v243 offset:24576
	s_waitcnt lgkmcnt(3)
	v_mfma_f32_32x32x16_bf16 v[130:145], v[194:197], v[178:181], v[130:145]
	s_waitcnt lgkmcnt(2)
	v_mfma_f32_32x32x16_bf16 v[130:145], v[198:201], v[182:185], v[130:145]
	s_waitcnt lgkmcnt(1)
	v_mfma_f32_32x32x16_bf16 v[130:145], v[202:205], v[186:189], v[130:145]
	s_waitcnt lgkmcnt(0)
	v_mfma_f32_32x32x16_bf16 v[130:145], v[206:209], v[190:193], v[130:145]
	s_setprio 0
	v_max3_f32 v194, v146, v147, v148
	v_max3_f32 v195, v154, v155, v156
	v_max3_f32 v194, v194, v149, v150
	v_max3_f32 v195, v195, v157, v158
	v_max3_f32 v194, v194, v151, v152
	v_max3_f32 v195, v195, v159, v160
	v_max_f32_e32 v194, v194, v153
	v_max_f32_e32 v195, v195, v161
	s_nop 4
	v_max3_f32 v196, v130, v131, v132
	v_max3_f32 v197, v138, v139, v140
	v_max3_f32 v196, v196, v133, v134
	v_max3_f32 v197, v197, v141, v142
	v_max3_f32 v196, v196, v135, v136
	v_max3_f32 v197, v197, v143, v144
	v_max_f32_e32 v196, v196, v137
	v_max_f32_e32 v197, v197, v145
	v_max3_f32 v194, v194, v195, v196
	v_max_f32_e32 v194, v194, v197
	v_mov_b32_e32 v195, v194
	s_nop 1
	v_permlane32_swap_b32_e32 v194, v195
	v_max_f32_e32 v194, v194, v195
	v_sub_f32_e32 v195, v194, v246
	v_cmp_ge_f32_e32 vcc, s63, v195
	s_cmp_eq_u64 vcc, exec
	s_cbranch_scc0 .Lda_slow_l0_4
	s_mov_b64 s[6:7], -1
	v_mov_b32_e32 v222, 1.0
	s_branch .LBB0_429
.Lda_slow_l0_4:
	v_max_f32_e32 v223, v246, v194
	v_sub_f32_e32 v194, v246, v223
	v_mul_f32_e32 v194, 0x3e0293ee, v194
	v_exp_f32_e32 v194, v194
	s_mov_b64 s[6:7], 0
	s_nop 0
	v_mov_b32_e32 v222, v194
	v_cmp_gt_f32_e32 vcc, 1.0, v222
	s_cbranch_vccz .LBB0_429
	s_and_saveexec_b64 s[58:59], s[4:5]
	s_cbranch_execz .LBB0_428
	ds_write_b32 v237, v222 offset:128
	s_branch .LBB0_428

; __device__ __forceinline__ int v_rd_base(int lane) { return ((lane & 3) << 3) | (((lane >> 2) & 3) << 6) | (((lane >> 4) & 1) << 5) | (((lane >> 5) & 1) << 8); }
; #define DPUB() do { asm volatile("s_waitcnt vmcnt(0)" ::: "memory"); __syncthreads(); } while (0)
; __device__ __forceinline__ void unit_body_da(const Unit& U, char* lds) {
;   int tid = threadIdx.x; asm volatile("" : "+v"(tid)); const int wid = __builtin_amdgcn_readfirstlane(tid >> 6), lane = tid & 63, r32 = lane & 31, hi = lane >> 5;
;   char* V_lds = lds; char* K_lds = lds + 2 * DA_VB;
;   float* ws = (float*)(lds + DA_WS_OFF) + wid * 64; float* li_l = ws; float* al_l = ws + 32;
;   float m_reg = -1e30f, l_reg = 0; f32x16 o[8] = {}; bf16x8 qr[8];
;   const bf16_t* Qw = U.Q + (long)(wid * QBLK + r32) * LDP + hi * 8;
; #pragma unroll
;   for (int d0 = 0; d0 < 8; ++d0) qr[d0] = ld8(Qw + d0 * 16);
;   const int vb0 = (int)(uintptr_t)V_lds + v_rd_base(lane);
;   const int ka0 = (int)(uintptr_t)K_lds + KSWZ(r32, hi * 16);
;   constexpr float C = SCALE * 1.4426950408889634f;
;   unsigned koff[2], voff[2][2];
; #pragma unroll
;   for (int i = 0; i < 2; ++i) { const int ob = (2 * wid + i) * 1024 + lane * 16;
;     { const int row = ob >> 8, cpos = (ob >> 4) & 15, c = cpos ^ (row & 7); koff[i] = (unsigned)(row * LDP + c * 8); }
;     { const int st = ob >> 9, kk = (st >> 2) * 8 + ((ob >> 6) & 7), c = (st & 3) * 32 + ((ob >> 1) & 31), k = (kk & ~0xC) | ((kk & 4) << 1) | ((kk & 8) >> 1);
;       voff[0][i] = (unsigned)(k * LDP + c); voff[1][i] = (unsigned)(k * LDP + 128 + c); } }
;   typedef __attribute__((address_space(3))) unsigned lds_u32;
;     ...
;   const int NT = U.nt;
;   DDMA(0, 0); DPUB();
.LBB0_1432:
	s_and_b64 vcc, exec, s[62:63]
	s_cbranch_vccz .LBB0_1404
	v_mov_b32_e32 v8, v210
	v_mov_b64_e32 v[2:3], s[56:57]
	v_readfirstlane_b32 s0, v8
	s_ashr_i32 s3, s0, 6
	s_and_b32 s0, s0, 0x3fffffc0
	s_lshl_b32 s0, s0, 2
	v_and_b32_e32 v234, 31, v8
	s_add_i32 s28, s0, 0
	s_lshl_b32 s60, s3, 5
	v_bfe_u32 v233, v8, 5, 1
	s_add_i32 s28, s28, 0x18000
	v_or_b32_e32 v0, s60, v234
	s_add_i32 s67, 0, 0x10000
	v_mad_i64_i32 v[2:3], s[0:1], v0, s92, v[2:3]
	v_lshlrev_b32_e32 v212, 4, v233
	v_mov_b32_e32 v213, v1
	s_cmp_lg_u32 s67, -1
	v_lshl_add_u64 v[2:3], v[2:3], 0, v[212:213]
	s_cselect_b32 s0, s67, 0
	s_lshl_b32 s29, s3, 11
	global_load_dwordx4 v[162:165], v[2:3], off
	global_load_dwordx4 v[166:169], v[2:3], off offset:32
	global_load_dwordx4 v[170:173], v[2:3], off offset:64
	global_load_dwordx4 v[174:177], v[2:3], off offset:96
	global_load_dwordx4 v[178:181], v[2:3], off offset:128
	global_load_dwordx4 v[182:185], v[2:3], off offset:160
	global_load_dwordx4 v[186:189], v[2:3], off offset:192
	global_load_dwordx4 v[190:193], v[2:3], off offset:224
	s_ashr_i32 s1, s29, 8
	v_lshrrev_b32_e32 v2, 1, v8
	v_and_b32_e32 v9, 63, v8
	v_bfe_u32 v0, v8, 2, 2
	s_and_b32 s3, s1, 0xfffff0
	v_and_b32_e32 v2, 8, v2
	s_waitcnt vmcnt(0)
	v_lshlrev_b32_e32 v12, 4, v9
	s_lshr_b32 s1, s1, 1
	v_or3_b32 v0, v2, v0, s3
	v_and_or_b32 v0, s1, 4, v0
	v_or_b32_e32 v5, 0x400, v12
	v_mul_i32_i24_e32 v13, 0x1800, v0
	v_or_b32_e32 v0, s29, v12
	v_or_b32_e32 v4, s29, v5
	v_and_b32_e32 v3, 15, v8
	v_ashrrev_i32_e32 v0, 8, v0
	v_ashrrev_i32_e32 v4, 8, v4
	v_bitop3_b32 v2, v0, v3, 15 bitop3:0x6c
	v_bitop3_b32 v3, v4, v3, 15 bitop3:0x6c
	v_mul_i32_i24_e32 v4, 0x1800, v4
	v_lshlrev_b32_e32 v10, 3, v9
	v_mul_i32_i24_e32 v0, 0x1800, v0
	v_lshl_or_b32 v4, v3, 3, v4
	v_lshrrev_b32_e32 v3, 4, v5
	v_and_b32_e32 v11, 24, v10
	v_lshl_or_b32 v0, v2, 3, v0
	v_and_b32_e32 v14, 32, v8
	v_and_b32_e32 v3, 0x60, v3
	s_add_i32 s61, s67, s29
	v_or3_b32 v2, v11, v14, v13
	v_or3_b32 v6, v11, v3, v13
	v_lshl_add_u64 v[214:215], v[0:1], 1, s[24:25]
	s_mov_b32 m0, s61
	v_mov_b32_e32 v3, v1
	s_add_i32 s62, s29, 0
	global_load_lds_dwordx4 v[214:215], off
	v_lshl_add_u64 v[2:3], v[2:3], 1, s[22:23]
	s_mov_b32 m0, s62
	s_add_i32 s63, s62, 0x4000
	s_or_b32 s66, s29, 0x400
	global_load_lds_dwordx4 v[2:3], off
	v_lshl_add_u64 v[2:3], v[2:3], 0, s[8:9]
	s_mov_b32 m0, s63
	v_mov_b32_e32 v5, v1
	s_add_i32 s67, s67, s66
	global_load_lds_dwordx4 v[2:3], off
	v_lshl_add_u64 v[216:217], v[4:5], 1, s[24:25]
	s_mov_b32 m0, s67
	v_mov_b32_e32 v7, v1
	s_add_i32 s68, s62, 0x400
	global_load_lds_dwordx4 v[216:217], off
	v_lshl_add_u64 v[2:3], v[6:7], 1, s[22:23]
	s_mov_b32 m0, s68
	s_add_i32 s69, s62, 0x4400
	global_load_lds_dwordx4 v[2:3], off
	v_lshl_add_u64 v[2:3], v[2:3], 0, s[8:9]
	s_mov_b32 m0, s69
	v_lshlrev_b32_e32 v0, 1, v8
	global_load_lds_dwordx4 v[2:3], off
	v_and_b32_e32 v0, 32, v0
	v_and_or_b32 v0, v12, s93, v0
	v_and_b32_e32 v2, 0x100, v10
	s_cmp_lg_u32 0, -1
	v_or3_b32 v0, v0, v2, v11
	s_cselect_b32 s3, 0, 0
	v_add_u32_e32 v213, s3, v0
	s_add_i32 s3, s3, 0x8000
	v_add_u32_e32 v244, s3, v0
	v_or3_b32 v0, v13, v14, v11
	s_movk_i32 s3, 0x60
	v_bitop3_b32 v3, v233, v8, 15 bitop3:0x78
	v_lshl_add_u64 v[218:219], v[0:1], 1, s[22:23]
	v_bitop3_b32 v0, v9, s3, 64 bitop3:0xc8
	v_lshlrev_b32_e32 v2, 8, v234
	v_lshlrev_b32_e32 v3, 4, v3
	v_or3_b32 v0, v13, v0, v11
	v_mov_b32_e32 v14, v1
	v_mov_b32_e32 v15, v1
	v_add3_u32 v235, v2, s0, v3
	s_waitcnt vmcnt(0)
	v_cmp_gt_u32_e64 s[0:1], 32, v9
	v_lshl_add_u64 v[220:221], v[0:1], 1, s[22:23]
	v_mov_b32_e32 v0, v1
	v_mov_b32_e32 v2, v1
	v_mov_b32_e32 v3, v1
	v_mov_b32_e32 v4, v1
	v_mov_b32_e32 v6, v1
	v_mov_b32_e32 v8, v1
	v_mov_b32_e32 v9, v1
	v_mov_b32_e32 v10, v1
	v_mov_b32_e32 v11, v1
	v_mov_b32_e32 v12, v1
	v_mov_b32_e32 v13, v1
	v_mov_b64_e32 v[128:129], v[14:15]
	v_mov_b64_e32 v[112:113], v[14:15]
	v_mov_b64_e32 v[96:97], v[14:15]
	v_mov_b64_e32 v[80:81], v[14:15]
	v_mov_b64_e32 v[64:65], v[14:15]
	v_mov_b64_e32 v[48:49], v[14:15]
	v_mov_b64_e32 v[32:33], v[14:15]
	v_mov_b64_e32 v[126:127], v[12:13]
	v_mov_b64_e32 v[124:125], v[10:11]
	v_mov_b64_e32 v[122:123], v[8:9]
	v_mov_b64_e32 v[120:121], v[6:7]
	v_mov_b64_e32 v[118:119], v[4:5]
	v_mov_b64_e32 v[116:117], v[2:3]
	v_mov_b64_e32 v[114:115], v[0:1]
	v_mov_b64_e32 v[110:111], v[12:13]
	v_mov_b64_e32 v[108:109], v[10:11]
	v_mov_b64_e32 v[106:107], v[8:9]
	v_mov_b64_e32 v[104:105], v[6:7]
	v_mov_b64_e32 v[102:103], v[4:5]
	v_mov_b64_e32 v[100:101], v[2:3]
	v_mov_b64_e32 v[98:99], v[0:1]
	v_mov_b64_e32 v[94:95], v[12:13]
	v_mov_b64_e32 v[92:93], v[10:11]
	v_mov_b64_e32 v[90:91], v[8:9]
	v_mov_b64_e32 v[88:89], v[6:7]
	v_mov_b64_e32 v[86:87], v[4:5]
	v_mov_b64_e32 v[84:85], v[2:3]
	v_mov_b64_e32 v[82:83], v[0:1]
	v_mov_b64_e32 v[78:79], v[12:13]
	v_mov_b64_e32 v[76:77], v[10:11]
	v_mov_b64_e32 v[74:75], v[8:9]
	v_mov_b64_e32 v[72:73], v[6:7]
	v_mov_b64_e32 v[70:71], v[4:5]
	v_mov_b64_e32 v[68:69], v[2:3]
	v_mov_b64_e32 v[66:67], v[0:1]
	v_mov_b64_e32 v[62:63], v[12:13]
	v_mov_b64_e32 v[60:61], v[10:11]
	v_mov_b64_e32 v[58:59], v[8:9]
	v_mov_b64_e32 v[56:57], v[6:7]
	v_mov_b64_e32 v[54:55], v[4:5]
	v_mov_b64_e32 v[52:53], v[2:3]
	v_mov_b64_e32 v[50:51], v[0:1]
	v_mov_b64_e32 v[46:47], v[12:13]
	v_mov_b64_e32 v[44:45], v[10:11]
	v_mov_b64_e32 v[42:43], v[8:9]
	v_mov_b64_e32 v[40:41], v[6:7]
	v_mov_b64_e32 v[38:39], v[4:5]
	v_mov_b64_e32 v[36:37], v[2:3]
	v_mov_b64_e32 v[34:35], v[0:1]
	v_mov_b64_e32 v[30:31], v[12:13]
	v_mov_b64_e32 v[28:29], v[10:11]
	v_mov_b64_e32 v[26:27], v[8:9]
	v_mov_b64_e32 v[24:25], v[6:7]
	v_mov_b64_e32 v[22:23], v[4:5]
	v_mov_b64_e32 v[20:21], v[2:3]
	v_mov_b64_e32 v[18:19], v[0:1]
	v_mov_b64_e32 v[16:17], v[14:15]
	s_mov_b32 s80, 2
	v_xor_b32_e32 v236, 32, v235
	v_xor_b32_e32 v238, 64, v235
	v_xor_b32_e32 v239, 0x60, v235
	v_xor_b32_e32 v240, 0x80, v235
	v_xor_b32_e32 v241, 0xa0, v235
	v_xor_b32_e32 v242, 0xc0, v235
	v_xor_b32_e32 v243, 0xe0, v235
	v_lshl_add_u32 v237, v234, 2, s28
	v_mov_b32_e32 v245, 0
	v_mov_b32_e32 v246, 0xf149f2ca
	s_mov_b64 s[22:23], 0
	v_mov_b64_e32 v[14:15], v[12:13]
	v_mov_b64_e32 v[12:13], v[10:11]
	v_mov_b64_e32 v[10:11], v[8:9]
	v_mov_b64_e32 v[8:9], v[6:7]
	v_mov_b64_e32 v[6:7], v[4:5]
	v_mov_b64_e32 v[4:5], v[2:3]
	v_mov_b64_e32 v[2:3], v[0:1]
	s_waitcnt vmcnt(0) lgkmcnt(0)
	s_barrier
	s_cmp_lt_u32 s29, 0x2000
	s_cbranch_scc1 .Lda_l1_lead_in
	s_barrier

; #define SBAR() __builtin_amdgcn_sched_barrier(0)
; __device__ __forceinline__ void partialSM(f32x16& p0, f32x16& p1, float& m_reg, float& mn, float& alpha) {
;     ...
;   float mnC = -mn * C;
; #pragma unroll
;   for (int r = 0; r < 16; ++r) p0[r] = fmaf(p0[r], C, mnC);
; #pragma unroll
;   for (int r = 0; r < 16; ++r) p1[r] = fmaf(p1[r], C, mnC);
; #pragma unroll
;   for (int r = 0; r < 16; ++r) p0[r] = __builtin_amdgcn_exp2f(p0[r]);
; }
; __device__ __forceinline__ void finishSM(f32x16& p0, f32x16& p1, float alpha, float& l_reg, bf16x8& pa0, bf16x8& pa1, bf16x8& pa2, bf16x8& pa3) {
; #pragma unroll
;   for (int r = 0; r < 16; ++r) p1[r] = __builtin_amdgcn_exp2f(p1[r]);
;   float ps = 0;
; #pragma unroll
;   for (int r = 0; r < 16; ++r) ps += p0[r];
; #pragma unroll
;   for (int r = 0; r < 16; ++r) ps += p1[r];
;   { auto rr = __builtin_amdgcn_permlane32_swap(__float_as_uint(ps), __float_as_uint(ps), false, false);
;     ps = __uint_as_float(rr[0]) + __uint_as_float(rr[1]); }
;   l_reg = l_reg * alpha + ps;
;     ...
;   PK4(p0, 0, pa0); PK4(p0, 8, pa1); PK4(p1, 0, pa2); PK4(p1, 8, pa3);
;     ...
; }
; template <int I> __device__ __forceinline__ void pv_step(f32x16* o, int vb, const bf16x8 (&pa)[4], s16x4 (&l)[3], s16x4 (&h)[3]) {
;   if constexpr (I + 2 < 32) pv_rd<(I + 2 < 32 ? I + 2 : 0)>(vb, l[(I + 2) % 3], h[(I + 2) % 3]);
;   if constexpr (I + 2 < 32) asm volatile("s_waitcnt lgkmcnt(4)" ::: "memory"); else if constexpr (I + 1 < 32) asm volatile("s_waitcnt lgkmcnt(2)" ::: "memory"); else asm volatile("s_waitcnt lgkmcnt(0)" ::: "memory");
;   SBAR();
;   const s16x4 L = l[I % 3], H = h[I % 3];
;   o[I >> 2] = __builtin_amdgcn_mfma_f32_32x32x16_bf16(pa[I & 3], (bf16x8){L[0], L[1], L[2], L[3], H[0], H[1], H[2], H[3]}, o[I >> 2], 0, 0, 0);
;   SBAR();
;   if constexpr (I + 1 < 32) pv_step<(I + 1 < 32 ? I + 1 : 31)>(o, vb, pa, l, h);
; }
; __device__ __forceinline__ void pv_all_rolling(f32x16* o, int vb, bf16x8 pa0, bf16x8 pa1, bf16x8 pa2, bf16x8 pa3) {
;   const bf16x8 pa[4] = {pa0, pa1, pa2, pa3}; s16x4 l[3], h[3];
;   asm volatile("s_waitcnt lgkmcnt(0)" ::: "memory");
;   pv_rd<0>(vb, l[0], h[0]); pv_rd<1>(vb, l[1], h[1]);
;   pv_step<0>(o, vb, pa, l, h);
.LBB0_1435:
	v_cndmask_b32_e64 v246, v223, v246, s[6:7]
	v_mul_f32_e32 v194, 0xbe0293ee, v246
	v_fmamk_f32 v146, v146, 0x3e0293ee, v194
	v_fmamk_f32 v147, v147, 0x3e0293ee, v194
	v_fmamk_f32 v148, v148, 0x3e0293ee, v194
	v_fmamk_f32 v149, v149, 0x3e0293ee, v194
	v_fmamk_f32 v150, v150, 0x3e0293ee, v194
	v_fmamk_f32 v151, v151, 0x3e0293ee, v194
	v_fmamk_f32 v152, v152, 0x3e0293ee, v194
	v_fmamk_f32 v153, v153, 0x3e0293ee, v194
	v_fmamk_f32 v154, v154, 0x3e0293ee, v194
	v_fmamk_f32 v155, v155, 0x3e0293ee, v194
	v_fmamk_f32 v156, v156, 0x3e0293ee, v194
	v_fmamk_f32 v157, v157, 0x3e0293ee, v194
	v_fmamk_f32 v158, v158, 0x3e0293ee, v194
	v_fmamk_f32 v159, v159, 0x3e0293ee, v194
	v_fmamk_f32 v160, v160, 0x3e0293ee, v194
	v_fmamk_f32 v161, v161, 0x3e0293ee, v194
	v_fmamk_f32 v130, v130, 0x3e0293ee, v194
	v_fmamk_f32 v131, v131, 0x3e0293ee, v194
	v_fmamk_f32 v132, v132, 0x3e0293ee, v194
	v_fmamk_f32 v133, v133, 0x3e0293ee, v194
	v_fmamk_f32 v134, v134, 0x3e0293ee, v194
	v_fmamk_f32 v135, v135, 0x3e0293ee, v194
	v_fmamk_f32 v136, v136, 0x3e0293ee, v194
	v_fmamk_f32 v137, v137, 0x3e0293ee, v194
	v_fmamk_f32 v138, v138, 0x3e0293ee, v194
	v_fmamk_f32 v139, v139, 0x3e0293ee, v194
	v_fmamk_f32 v140, v140, 0x3e0293ee, v194
	v_fmamk_f32 v141, v141, 0x3e0293ee, v194
	v_fmamk_f32 v142, v142, 0x3e0293ee, v194
	v_fmamk_f32 v143, v143, 0x3e0293ee, v194
	v_fmamk_f32 v144, v144, 0x3e0293ee, v194
	v_fmac_f32_e32 v194, 0x3e0293ee, v145
	v_exp_f32_e32 v145, v146
	v_exp_f32_e32 v146, v147
	v_exp_f32_e32 v147, v148
	v_exp_f32_e32 v148, v149
	v_exp_f32_e32 v149, v150
	v_exp_f32_e32 v150, v151
	v_exp_f32_e32 v151, v152
	v_exp_f32_e32 v152, v153
	v_exp_f32_e32 v153, v154
	v_exp_f32_e32 v154, v155
	v_exp_f32_e32 v155, v156
	v_exp_f32_e32 v156, v157
	v_exp_f32_e32 v157, v158
	v_exp_f32_e32 v158, v159
	v_exp_f32_e32 v159, v160
	v_exp_f32_e32 v160, v161
	v_add_f32_e32 v161, v247, v248
	v_fmac_f32_e32 v161, v245, v0
	v_exp_f32_e32 v0, v130
	v_add_f32_e32 v130, 0, v145
	v_add_f32_e32 v130, v146, v130
	v_add_f32_e32 v130, v147, v130
	v_add_f32_e32 v130, v148, v130
	v_add_f32_e32 v130, v149, v130
	s_waitcnt vmcnt(0)
	s_barrier
	s_setprio 0
	v_add_f32_e32 v130, v150, v130
	v_add_f32_e32 v130, v151, v130
	v_add_f32_e32 v130, v152, v130
	v_add_f32_e32 v130, v153, v130
	v_add_f32_e32 v130, v154, v130
	v_add_f32_e32 v130, v155, v130
	v_add_f32_e32 v130, v156, v130
	v_add_f32_e32 v130, v157, v130
	v_exp_f32_e32 v195, v131
	v_add_f32_e32 v130, v158, v130
	v_exp_f32_e32 v196, v132
	v_add_f32_e32 v130, v159, v130
	v_exp_f32_e32 v197, v133
	v_add_f32_e32 v130, v160, v130
	v_exp_f32_e32 v198, v134
	v_add_f32_e32 v130, v0, v130
	v_exp_f32_e32 v199, v135
	v_add_f32_e32 v130, v195, v130
	v_exp_f32_e32 v200, v136
	v_add_f32_e32 v130, v196, v130
	v_exp_f32_e32 v201, v137
	v_add_f32_e32 v130, v197, v130
	v_exp_f32_e32 v202, v138
	v_add_f32_e32 v130, v198, v130
	v_exp_f32_e32 v203, v139
	v_add_f32_e32 v130, v199, v130
	v_exp_f32_e32 v204, v140
	v_add_f32_e32 v130, v200, v130
	v_exp_f32_e32 v205, v141
	v_add_f32_e32 v130, v201, v130
	v_exp_f32_e32 v206, v142
	v_add_f32_e32 v130, v202, v130
	v_exp_f32_e32 v207, v143
	v_add_f32_e32 v130, v203, v130
	v_exp_f32_e32 v208, v144
	v_add_f32_e32 v130, v204, v130
	v_exp_f32_e32 v194, v194
	v_add_f32_e32 v130, v205, v130
	v_add_f32_e32 v130, v206, v130
	v_add_f32_e32 v130, v207, v130
	v_add_f32_e32 v130, v208, v130
	v_add_f32_e32 v130, v194, v130
	v_mov_b32_e32 v131, v130
	s_nop 1
	v_permlane32_swap_b32_e32 v130, v131
	v_add_f32_e32 v245, v130, v131
	v_fmac_f32_e32 v245, v161, v222
	v_cvt_pk_bf16_f32 v130, v145, v146
	v_cvt_pk_bf16_f32 v131, v147, v148
	v_cvt_pk_bf16_f32 v132, v149, v150
	v_cvt_pk_bf16_f32 v133, v151, v152
	v_cvt_pk_bf16_f32 v134, v153, v154
	v_cvt_pk_bf16_f32 v135, v155, v156
	v_cvt_pk_bf16_f32 v136, v157, v158
	v_cvt_pk_bf16_f32 v137, v159, v160
	v_cvt_pk_bf16_f32 v138, v0, v195
	v_cvt_pk_bf16_f32 v139, v196, v197
	v_cvt_pk_bf16_f32 v140, v198, v199
	v_cvt_pk_bf16_f32 v141, v200, v201
	v_cvt_pk_bf16_f32 v142, v202, v203
	v_cvt_pk_bf16_f32 v143, v204, v205
	v_cvt_pk_bf16_f32 v144, v206, v207
	v_cvt_pk_bf16_f32 v145, v208, v194
	s_nop 0
	v_permlane32_swap_b32_e32 v130, v132
	v_permlane32_swap_b32_e32 v131, v133
	v_permlane32_swap_b32_e32 v134, v136
	v_permlane32_swap_b32_e32 v135, v137
	v_permlane32_swap_b32_e32 v138, v140
	v_permlane32_swap_b32_e32 v139, v141
	v_permlane32_swap_b32_e32 v142, v144
	v_permlane32_swap_b32_e32 v143, v145
	s_waitcnt lgkmcnt(0)
	ds_read_b64_tr_b16 v[146:147], v244 offset:0
	ds_read_b64_tr_b16 v[148:149], v244 offset:2048
	ds_read_b64_tr_b16 v[150:151], v244 offset:4096
	ds_read_b64_tr_b16 v[152:153], v244 offset:6144
	ds_read_b64_tr_b16 v[154:155], v244 offset:8192
	ds_read_b64_tr_b16 v[156:157], v244 offset:10240
	ds_read_b64_tr_b16 v[158:159], v244 offset:12288
	ds_read_b64_tr_b16 v[160:161], v244 offset:14336
	ds_read_b64_tr_b16 v[194:195], v244 offset:512
	ds_read_b64_tr_b16 v[196:197], v244 offset:2560
	v_lshl_add_u64 v[232:233], v[218:219], 0, s[22:23]
	v_lshl_add_u64 v[232:233], v[232:233], 0, s[14:15]
	s_mov_b32 m0, s62
	s_nop 0
	global_load_lds_dwordx4 v[232:233], off
	s_waitcnt lgkmcnt(8)
	s_nop 0
	v_mfma_f32_32x32x16_bf16 v[114:129], v[130:133], v[146:149], v[114:129]
	ds_read_b64_tr_b16 v[198:199], v244 offset:4608
	ds_read_b64_tr_b16 v[200:201], v244 offset:6656
	v_lshl_add_u64 v[232:233], v[218:219], 0, s[22:23]
	v_lshl_add_u64 v[232:233], v[232:233], 0, s[16:17]
	s_mov_b32 m0, s63
	s_nop 0
	global_load_lds_dwordx4 v[232:233], off
	s_waitcnt lgkmcnt(8)
; #define SBAR() __builtin_amdgcn_sched_barrier(0)
; #define DPUB() do { asm volatile("s_waitcnt vmcnt(0)" ::: "memory"); __syncthreads(); } while (0)
; #define DTILE(b) do { f32x16 p0 = f32x16{}, p1 = f32x16{}; float mn, al; bf16x8 pa0, pa1, pa2, pa3; \
;     qkt_rolling<(b) * DA_KB>(p0, p1, ka0, qr); partialSM(p0, p1, m_reg, mn, al); DRESC(al); finishSM(p0, p1, al, l_reg, pa0, pa1, pa2, pa3); SBAR(); \
;     pv_all_rolling(o, vb0 + (b) * DA_VB, pa0, pa1, pa2, pa3); } while (0)
; template <int I> __device__ __forceinline__ void pv_step(f32x16* o, int vb, const bf16x8 (&pa)[4], s16x4 (&l)[3], s16x4 (&h)[3]) {
;   if constexpr (I + 2 < 32) pv_rd<(I + 2 < 32 ? I + 2 : 0)>(vb, l[(I + 2) % 3], h[(I + 2) % 3]);
;   if constexpr (I + 2 < 32) asm volatile("s_waitcnt lgkmcnt(4)" ::: "memory"); else if constexpr (I + 1 < 32) asm volatile("s_waitcnt lgkmcnt(2)" ::: "memory"); else asm volatile("s_waitcnt lgkmcnt(0)" ::: "memory");
;   SBAR();
;   const s16x4 L = l[I % 3], H = h[I % 3];
;   o[I >> 2] = __builtin_amdgcn_mfma_f32_32x32x16_bf16(pa[I & 3], (bf16x8){L[0], L[1], L[2], L[3], H[0], H[1], H[2], H[3]}, o[I >> 2], 0, 0, 0);
;   SBAR();
;   if constexpr (I + 1 < 32) pv_step<(I + 1 < 32 ? I + 1 : 31)>(o, vb, pa, l, h);
; }
; __device__ __forceinline__ void pv_all_rolling(f32x16* o, int vb, bf16x8 pa0, bf16x8 pa1, bf16x8 pa2, bf16x8 pa3) {
;   const bf16x8 pa[4] = {pa0, pa1, pa2, pa3}; s16x4 l[3], h[3];
;   asm volatile("s_waitcnt lgkmcnt(0)" ::: "memory");
;   pv_rd<0>(vb, l[0], h[0]); pv_rd<1>(vb, l[1], h[1]);
;   pv_step<0>(o, vb, pa, l, h);
; __device__ __forceinline__ void unit_body_da(const Unit& U, char* lds) {
;     ...
;   for (int j = 0; j < NT; j += 2) {
;     DDMA(j + 1, 1); SBAR();
;     DTILE(0); SBAR(); DPUB();
;     if (j + 2 < NT) DDMA(j + 2, 0); SBAR();
;     DTILE(1); SBAR(); DPUB();
;   }
	v_mfma_f32_32x32x16_bf16 v[114:129], v[134:137], v[150:153], v[114:129]
	ds_read_b64_tr_b16 v[202:203], v244 offset:8704
	ds_read_b64_tr_b16 v[204:205], v244 offset:10752
	v_lshl_add_u64 v[232:233], v[220:221], 0, s[22:23]
	v_lshl_add_u64 v[232:233], v[232:233], 0, s[14:15]
	s_mov_b32 m0, s68
	s_nop 0
	global_load_lds_dwordx4 v[232:233], off
	s_waitcnt lgkmcnt(8)
	v_mfma_f32_32x32x16_bf16 v[114:129], v[138:141], v[154:157], v[114:129]
	ds_read_b64_tr_b16 v[206:207], v244 offset:12800
	ds_read_b64_tr_b16 v[208:209], v244 offset:14848
	v_lshl_add_u64 v[232:233], v[220:221], 0, s[22:23]
	v_lshl_add_u64 v[232:233], v[232:233], 0, s[16:17]
	s_mov_b32 m0, s69
	s_nop 0
	global_load_lds_dwordx4 v[232:233], off
	s_waitcnt lgkmcnt(8)
	v_mfma_f32_32x32x16_bf16 v[114:129], v[142:145], v[158:161], v[114:129]
	ds_read_b64_tr_b16 v[146:147], v244 offset:1024
	ds_read_b64_tr_b16 v[148:149], v244 offset:3072
	s_waitcnt lgkmcnt(8)
	v_mfma_f32_32x32x16_bf16 v[98:113], v[130:133], v[194:197], v[98:113]
	ds_read_b64_tr_b16 v[150:151], v244 offset:5120
	ds_read_b64_tr_b16 v[152:153], v244 offset:7168
	s_waitcnt lgkmcnt(8)
	v_mfma_f32_32x32x16_bf16 v[98:113], v[134:137], v[198:201], v[98:113]
	ds_read_b64_tr_b16 v[154:155], v244 offset:9216
	ds_read_b64_tr_b16 v[156:157], v244 offset:11264
	s_waitcnt lgkmcnt(8)
	v_mfma_f32_32x32x16_bf16 v[98:113], v[138:141], v[202:205], v[98:113]
	ds_read_b64_tr_b16 v[158:159], v244 offset:13312
	ds_read_b64_tr_b16 v[160:161], v244 offset:15360
	s_waitcnt lgkmcnt(8)
	v_mfma_f32_32x32x16_bf16 v[98:113], v[142:145], v[206:209], v[98:113]
	ds_read_b64_tr_b16 v[194:195], v244 offset:1536
	ds_read_b64_tr_b16 v[196:197], v244 offset:3584
	s_waitcnt lgkmcnt(8)
	v_mfma_f32_32x32x16_bf16 v[82:97], v[130:133], v[146:149], v[82:97]
	ds_read_b64_tr_b16 v[198:199], v244 offset:5632
	ds_read_b64_tr_b16 v[200:201], v244 offset:7680
	s_waitcnt lgkmcnt(8)
	v_mfma_f32_32x32x16_bf16 v[82:97], v[134:137], v[150:153], v[82:97]
	ds_read_b64_tr_b16 v[202:203], v244 offset:9728
	ds_read_b64_tr_b16 v[204:205], v244 offset:11776
	s_waitcnt lgkmcnt(8)
	v_mfma_f32_32x32x16_bf16 v[82:97], v[138:141], v[154:157], v[82:97]
	ds_read_b64_tr_b16 v[206:207], v244 offset:13824
	ds_read_b64_tr_b16 v[208:209], v244 offset:15872
	s_waitcnt lgkmcnt(8)
	v_mfma_f32_32x32x16_bf16 v[82:97], v[142:145], v[158:161], v[82:97]
	ds_read_b64_tr_b16 v[146:147], v244 offset:16384
	ds_read_b64_tr_b16 v[148:149], v244 offset:18432
	s_waitcnt lgkmcnt(8)
	v_mfma_f32_32x32x16_bf16 v[66:81], v[130:133], v[194:197], v[66:81]
	ds_read_b64_tr_b16 v[150:151], v244 offset:20480
	ds_read_b64_tr_b16 v[152:153], v244 offset:22528
	s_waitcnt lgkmcnt(8)
	v_mfma_f32_32x32x16_bf16 v[66:81], v[134:137], v[198:201], v[66:81]
	ds_read_b64_tr_b16 v[154:155], v244 offset:24576
	ds_read_b64_tr_b16 v[156:157], v244 offset:26624
	s_waitcnt lgkmcnt(8)
	v_mfma_f32_32x32x16_bf16 v[66:81], v[138:141], v[202:205], v[66:81]
	ds_read_b64_tr_b16 v[158:159], v244 offset:28672
	ds_read_b64_tr_b16 v[160:161], v244 offset:30720
	s_waitcnt lgkmcnt(8)
	v_mfma_f32_32x32x16_bf16 v[66:81], v[142:145], v[206:209], v[66:81]
	ds_read_b64_tr_b16 v[194:195], v244 offset:16896
	ds_read_b64_tr_b16 v[196:197], v244 offset:18944
	s_waitcnt lgkmcnt(8)
	v_mfma_f32_32x32x16_bf16 v[50:65], v[130:133], v[146:149], v[50:65]
	ds_read_b64_tr_b16 v[198:199], v244 offset:20992
	ds_read_b64_tr_b16 v[200:201], v244 offset:23040
	s_waitcnt lgkmcnt(8)
	v_mfma_f32_32x32x16_bf16 v[50:65], v[134:137], v[150:153], v[50:65]
	ds_read_b64_tr_b16 v[202:203], v244 offset:25088
	ds_read_b64_tr_b16 v[204:205], v244 offset:27136
	s_waitcnt lgkmcnt(8)
	v_mfma_f32_32x32x16_bf16 v[50:65], v[138:141], v[154:157], v[50:65]
	ds_read_b64_tr_b16 v[206:207], v244 offset:29184
	ds_read_b64_tr_b16 v[208:209], v244 offset:31232
	s_waitcnt lgkmcnt(8)
	v_mfma_f32_32x32x16_bf16 v[50:65], v[142:145], v[158:161], v[50:65]
	ds_read_b64_tr_b16 v[146:147], v244 offset:17408
	ds_read_b64_tr_b16 v[148:149], v244 offset:19456
	s_waitcnt lgkmcnt(8)
	v_mfma_f32_32x32x16_bf16 v[34:49], v[130:133], v[194:197], v[34:49]
	ds_read_b64_tr_b16 v[150:151], v244 offset:21504
	ds_read_b64_tr_b16 v[152:153], v244 offset:23552
	s_waitcnt lgkmcnt(8)
	v_mfma_f32_32x32x16_bf16 v[34:49], v[134:137], v[198:201], v[34:49]
	ds_read_b64_tr_b16 v[154:155], v244 offset:25600
	ds_read_b64_tr_b16 v[156:157], v244 offset:27648
	s_waitcnt lgkmcnt(8)
	v_mfma_f32_32x32x16_bf16 v[34:49], v[138:141], v[202:205], v[34:49]
	ds_read_b64_tr_b16 v[158:159], v244 offset:29696
	ds_read_b64_tr_b16 v[160:161], v244 offset:31744
	s_waitcnt lgkmcnt(8)
	v_mfma_f32_32x32x16_bf16 v[34:49], v[142:145], v[206:209], v[34:49]
	ds_read_b64_tr_b16 v[194:195], v244 offset:17920
	ds_read_b64_tr_b16 v[196:197], v244 offset:19968
	s_waitcnt lgkmcnt(8)
	v_mfma_f32_32x32x16_bf16 v[18:33], v[130:133], v[146:149], v[18:33]
	ds_read_b64_tr_b16 v[198:199], v244 offset:22016
	ds_read_b64_tr_b16 v[200:201], v244 offset:24064
	s_waitcnt lgkmcnt(8)
	v_mfma_f32_32x32x16_bf16 v[18:33], v[134:137], v[150:153], v[18:33]
	ds_read_b64_tr_b16 v[202:203], v244 offset:26112
	ds_read_b64_tr_b16 v[204:205], v244 offset:28160
	s_waitcnt lgkmcnt(8)
	v_mfma_f32_32x32x16_bf16 v[18:33], v[138:141], v[154:157], v[18:33]
	ds_read_b64_tr_b16 v[206:207], v244 offset:30208
	ds_read_b64_tr_b16 v[208:209], v244 offset:32256
	s_waitcnt lgkmcnt(8)
	v_mfma_f32_32x32x16_bf16 v[18:33], v[142:145], v[158:161], v[18:33]
	s_waitcnt lgkmcnt(6)
	v_mfma_f32_32x32x16_bf16 v[2:17], v[130:133], v[194:197], v[2:17]
	s_waitcnt lgkmcnt(4)
	v_mfma_f32_32x32x16_bf16 v[2:17], v[134:137], v[198:201], v[2:17]
	s_waitcnt lgkmcnt(2)
	v_mfma_f32_32x32x16_bf16 v[2:17], v[138:141], v[202:205], v[2:17]
	s_waitcnt lgkmcnt(0)
	v_mfma_f32_32x32x16_bf16 v[2:17], v[142:145], v[206:209], v[2:17]
	s_waitcnt vmcnt(0)
	s_add_u32 s22, s22, 0x180000
	s_addc_u32 s23, s23, 0
	s_add_i32 s80, s80, 2
	s_and_b64 vcc, exec, s[24:25]
	s_waitcnt vmcnt(0) lgkmcnt(0)
	s_barrier
	s_cbranch_vccnz .LBB0_1445
; #define SBAR() __builtin_amdgcn_sched_barrier(0)
; template <int OFF> __device__ __forceinline__ bf16x8 k_read(int a) { bf16x8 r; asm volatile("ds_read_b128 %0, %1 offset:%2" : "=&v"(r) : "v"(a), "i"(OFF) : "memory"); return r; }
; __device__ __forceinline__ void partialSM(f32x16& p0, f32x16& p1, float& m_reg, float& mn, float& alpha) {
;   constexpr float C = SCALE * 1.4426950408889634f;
;   float pmax = p0[0];
; #pragma unroll
;   for (int r = 1; r < 16; ++r) pmax = fmaxf(pmax, p0[r]);
; #pragma unroll
;   for (int r = 0; r < 16; ++r) pmax = fmaxf(pmax, p1[r]);
;   { auto rr = __builtin_amdgcn_permlane32_swap(__float_as_uint(pmax), __float_as_uint(pmax), false, false);
;     pmax = fmaxf(__uint_as_float(rr[0]), __uint_as_float(rr[1])); }
;   if (__builtin_expect(__all(pmax - m_reg <= THR / SCALE), 1)) { mn = m_reg; alpha = 1.f; }
;   else { mn = fmaxf(m_reg, pmax); alpha = __builtin_amdgcn_exp2f((m_reg - mn) * C); m_reg = mn; }
; template <int BUFOFF, int D0> __device__ __forceinline__ void qk_step(f32x16& p0, f32x16& p1, int ka0, const bf16x8 (&qr)[8], bf16x8 (&k0)[2], bf16x8 (&k1)[2]) {
;   if constexpr (D0 + 1 < 8) { const int a_ = ka0 ^ ((D0 + 1) << 5); k0[(D0 + 1) & 1] = k_read<BUFOFF>(a_); k1[(D0 + 1) & 1] = k_read<BUFOFF + 8192>(a_); }
;   if constexpr (D0 + 1 < 8) asm volatile("s_waitcnt lgkmcnt(2)" ::: "memory"); else asm volatile("s_waitcnt lgkmcnt(0)" ::: "memory");
;   SBAR();
;   p0 = __builtin_amdgcn_mfma_f32_32x32x16_bf16(k0[D0 & 1], qr[D0], p0, 0, 0, 0);
;   p1 = __builtin_amdgcn_mfma_f32_32x32x16_bf16(k1[D0 & 1], qr[D0], p1, 0, 0, 0);
;   SBAR();
;   if constexpr (D0 + 1 < 8) qk_step<BUFOFF, (D0 + 1 < 8 ? D0 + 1 : 7)>(p0, p1, ka0, qr, k0, k1);
; }
; template <int BUFOFF> __device__ __forceinline__ void qkt_rolling(f32x16& p0, f32x16& p1, int ka0, const bf16x8 (&qr)[8]) {
;   bf16x8 k0[2], k1[2];
;   asm volatile("s_waitcnt lgkmcnt(0)" ::: "memory");
;   k0[0] = k_read<BUFOFF>(ka0); k1[0] = k_read<BUFOFF + 8192>(ka0);
;   qk_step<BUFOFF, 0>(p0, p1, ka0, qr, k0, k1);
; }
.LBB0_1436:
	s_setprio 1
	v_lshl_add_u64 v[224:225], v[214:215], 0, s[22:23]
	v_lshl_add_u64 v[228:229], v[216:217], 0, s[22:23]
	s_waitcnt lgkmcnt(0)
	ds_read_b128 v[194:197], v235 offset:0
	ds_read_b128 v[198:201], v236 offset:0
	ds_read_b128 v[202:205], v238 offset:0
	ds_read_b128 v[206:209], v239 offset:0
	ds_read_b128 v[130:133], v240 offset:0
	ds_read_b128 v[134:137], v241 offset:0
	ds_read_b128 v[138:141], v242 offset:0
	ds_read_b128 v[142:145], v243 offset:0
	v_lshl_add_u64 v[232:233], v[224:225], 0, s[10:11]
	s_add_i32 m0, s94, s29
	s_nop 0
	global_load_lds_dwordx4 v[232:233], off
	v_lshl_add_u64 v[232:233], v[228:229], 0, s[10:11]
	s_add_i32 m0, s94, s66
	s_nop 0
	global_load_lds_dwordx4 v[232:233], off
	s_waitcnt lgkmcnt(7)
	s_nop 0
	v_mfma_f32_32x32x16_bf16 v[146:161], v[194:197], v[162:165], 0
	ds_read_b128 v[194:197], v235 offset:8192
	s_waitcnt lgkmcnt(7)
	v_mfma_f32_32x32x16_bf16 v[146:161], v[198:201], v[166:169], v[146:161]
	ds_read_b128 v[198:201], v236 offset:8192
	s_waitcnt lgkmcnt(7)
	v_mfma_f32_32x32x16_bf16 v[146:161], v[202:205], v[170:173], v[146:161]
	ds_read_b128 v[202:205], v238 offset:8192
	s_waitcnt lgkmcnt(7)
	v_mfma_f32_32x32x16_bf16 v[146:161], v[206:209], v[174:177], v[146:161]
	ds_read_b128 v[206:209], v239 offset:8192
	s_waitcnt lgkmcnt(7)
	v_mfma_f32_32x32x16_bf16 v[146:161], v[130:133], v[178:181], v[146:161]
	s_waitcnt lgkmcnt(6)
	v_mfma_f32_32x32x16_bf16 v[146:161], v[134:137], v[182:185], v[146:161]
	s_waitcnt lgkmcnt(5)
	v_mfma_f32_32x32x16_bf16 v[146:161], v[138:141], v[186:189], v[146:161]
	s_waitcnt lgkmcnt(4)
	v_mfma_f32_32x32x16_bf16 v[146:161], v[142:145], v[190:193], v[146:161]
	s_waitcnt lgkmcnt(3)
	v_mfma_f32_32x32x16_bf16 v[130:145], v[194:197], v[162:165], 0
	ds_read_b128 v[194:197], v240 offset:8192
	s_waitcnt lgkmcnt(3)
	v_mfma_f32_32x32x16_bf16 v[130:145], v[198:201], v[166:169], v[130:145]
	ds_read_b128 v[198:201], v241 offset:8192
	s_waitcnt lgkmcnt(3)
	v_mfma_f32_32x32x16_bf16 v[130:145], v[202:205], v[170:173], v[130:145]
	ds_read_b128 v[202:205], v242 offset:8192
	s_waitcnt lgkmcnt(3)
	v_mfma_f32_32x32x16_bf16 v[130:145], v[206:209], v[174:177], v[130:145]
	ds_read_b128 v[206:209], v243 offset:8192
	s_waitcnt lgkmcnt(3)
	v_mfma_f32_32x32x16_bf16 v[130:145], v[194:197], v[178:181], v[130:145]
	s_waitcnt lgkmcnt(2)
	v_mfma_f32_32x32x16_bf16 v[130:145], v[198:201], v[182:185], v[130:145]
	s_waitcnt lgkmcnt(1)
	v_mfma_f32_32x32x16_bf16 v[130:145], v[202:205], v[186:189], v[130:145]
	s_waitcnt lgkmcnt(0)
	v_mfma_f32_32x32x16_bf16 v[130:145], v[206:209], v[190:193], v[130:145]
	s_setprio 0
	v_max3_f32 v0, v146, v147, v148
	v_max3_f32 v194, v154, v155, v156
	v_max3_f32 v0, v0, v149, v150
	v_max3_f32 v194, v194, v157, v158
	v_max3_f32 v0, v0, v151, v152
	v_max3_f32 v194, v194, v159, v160
	v_max_f32_e32 v0, v0, v153
	v_max_f32_e32 v194, v194, v161
	s_nop 4
	v_max3_f32 v196, v130, v131, v132
	v_max3_f32 v197, v138, v139, v140
	v_max3_f32 v196, v196, v133, v134
	v_max3_f32 v197, v197, v141, v142
	v_max3_f32 v196, v196, v135, v136
	v_max3_f32 v197, v197, v143, v144
	v_max_f32_e32 v196, v196, v137
	v_max_f32_e32 v197, v197, v145
	v_max3_f32 v0, v0, v194, v196
	v_max_f32_e32 v0, v0, v197
	v_mov_b32_e32 v194, v0
	s_nop 1
	v_permlane32_swap_b32_e32 v0, v194
	v_max_f32_e32 v0, v0, v194
	v_sub_f32_e32 v194, v0, v246
	v_cmp_ge_f32_e32 vcc, s95, v194
	s_cmp_eq_u64 vcc, exec
	s_cbranch_scc0 .Lda_slow_l1_1
	s_mov_b64 s[6:7], -1
	v_mov_b32_e32 v0, 1.0
	s_branch .LBB0_1440
.Lda_slow_l1_1:
	v_max_f32_e32 v247, v246, v0
	v_sub_f32_e32 v0, v246, v247
	v_mul_f32_e32 v0, 0x3e0293ee, v0
	v_exp_f32_e32 v0, v0
	s_mov_b64 s[6:7], 0
	s_nop 0
	v_cmp_gt_f32_e32 vcc, 1.0, v0
	s_cbranch_vccz .LBB0_1440
	s_and_saveexec_b64 s[24:25], s[0:1]
	ds_write_b32 v237, v0 offset:128
	s_or_b64 exec, exec, s[24:25]
	s_waitcnt lgkmcnt(0)
	v_add_u32_e32 v194, s28, v212
	ds_read_b128 v[206:209], v194 offset:224
	ds_read_b128 v[202:205], v194 offset:192
	ds_read_b128 v[198:201], v194 offset:160
	ds_read_b128 v[194:197], v194 offset:128
	s_waitcnt lgkmcnt(0)
	v_pk_mul_f32 v[126:127], v[126:127], v[206:207]
	v_pk_mul_f32 v[122:123], v[122:123], v[202:203]
	v_pk_mul_f32 v[118:119], v[118:119], v[198:199]
	v_pk_mul_f32 v[128:129], v[128:129], v[208:209]
	v_pk_mul_f32 v[124:125], v[124:125], v[204:205]
	v_pk_mul_f32 v[120:121], v[120:121], v[200:201]
	v_pk_mul_f32 v[116:117], v[116:117], v[196:197]
	v_pk_mul_f32 v[114:115], v[114:115], v[194:195]
	v_pk_mul_f32 v[110:111], v[110:111], v[206:207]
	v_pk_mul_f32 v[106:107], v[106:107], v[202:203]
	v_pk_mul_f32 v[102:103], v[102:103], v[198:199]
	v_pk_mul_f32 v[112:113], v[112:113], v[208:209]
	v_pk_mul_f32 v[108:109], v[108:109], v[204:205]
	v_pk_mul_f32 v[104:105], v[104:105], v[200:201]
	v_pk_mul_f32 v[100:101], v[100:101], v[196:197]
	v_pk_mul_f32 v[98:99], v[98:99], v[194:195]
	v_pk_mul_f32 v[94:95], v[94:95], v[206:207]
	v_pk_mul_f32 v[90:91], v[90:91], v[202:203]
	v_pk_mul_f32 v[86:87], v[86:87], v[198:199]
	v_pk_mul_f32 v[96:97], v[96:97], v[208:209]
	v_pk_mul_f32 v[92:93], v[92:93], v[204:205]
	v_pk_mul_f32 v[88:89], v[88:89], v[200:201]
	v_pk_mul_f32 v[84:85], v[84:85], v[196:197]
	v_pk_mul_f32 v[82:83], v[82:83], v[194:195]
	v_pk_mul_f32 v[78:79], v[78:79], v[206:207]
	v_pk_mul_f32 v[74:75], v[74:75], v[202:203]
	v_pk_mul_f32 v[70:71], v[70:71], v[198:199]
	v_pk_mul_f32 v[80:81], v[80:81], v[208:209]
	v_pk_mul_f32 v[76:77], v[76:77], v[204:205]
	v_pk_mul_f32 v[72:73], v[72:73], v[200:201]
	v_pk_mul_f32 v[68:69], v[68:69], v[196:197]
	v_pk_mul_f32 v[66:67], v[66:67], v[194:195]
	v_pk_mul_f32 v[62:63], v[62:63], v[206:207]
	v_pk_mul_f32 v[58:59], v[58:59], v[202:203]
	v_pk_mul_f32 v[54:55], v[54:55], v[198:199]
	v_pk_mul_f32 v[64:65], v[64:65], v[208:209]
	v_pk_mul_f32 v[60:61], v[60:61], v[204:205]
	v_pk_mul_f32 v[56:57], v[56:57], v[200:201]
	v_pk_mul_f32 v[52:53], v[52:53], v[196:197]
	v_pk_mul_f32 v[50:51], v[50:51], v[194:195]
	v_pk_mul_f32 v[46:47], v[46:47], v[206:207]
	v_pk_mul_f32 v[42:43], v[42:43], v[202:203]
	v_pk_mul_f32 v[38:39], v[38:39], v[198:199]
	v_pk_mul_f32 v[48:49], v[48:49], v[208:209]
	v_pk_mul_f32 v[44:45], v[44:45], v[204:205]
	v_pk_mul_f32 v[40:41], v[40:41], v[200:201]
	v_pk_mul_f32 v[36:37], v[36:37], v[196:197]
	v_pk_mul_f32 v[34:35], v[34:35], v[194:195]
	v_pk_mul_f32 v[30:31], v[30:31], v[206:207]
	v_pk_mul_f32 v[26:27], v[26:27], v[202:203]
	v_pk_mul_f32 v[22:23], v[22:23], v[198:199]
	v_pk_mul_f32 v[32:33], v[32:33], v[208:209]
	v_pk_mul_f32 v[28:29], v[28:29], v[204:205]
	v_pk_mul_f32 v[24:25], v[24:25], v[200:201]
	v_pk_mul_f32 v[20:21], v[20:21], v[196:197]
	v_pk_mul_f32 v[18:19], v[18:19], v[194:195]
	v_pk_mul_f32 v[14:15], v[14:15], v[206:207]
	v_pk_mul_f32 v[10:11], v[10:11], v[202:203]
	v_pk_mul_f32 v[6:7], v[6:7], v[198:199]
	v_pk_mul_f32 v[16:17], v[16:17], v[208:209]
	v_pk_mul_f32 v[12:13], v[12:13], v[204:205]
	v_pk_mul_f32 v[8:9], v[8:9], v[200:201]
	v_pk_mul_f32 v[4:5], v[4:5], v[196:197]
	v_pk_mul_f32 v[2:3], v[2:3], v[194:195]
; #define SBAR() __builtin_amdgcn_sched_barrier(0)
; __device__ __forceinline__ void partialSM(f32x16& p0, f32x16& p1, float& m_reg, float& mn, float& alpha) {
;     ...
;   float mnC = -mn * C;
; #pragma unroll
;   for (int r = 0; r < 16; ++r) p0[r] = fmaf(p0[r], C, mnC);
; #pragma unroll
;   for (int r = 0; r < 16; ++r) p1[r] = fmaf(p1[r], C, mnC);
; #pragma unroll
;   for (int r = 0; r < 16; ++r) p0[r] = __builtin_amdgcn_exp2f(p0[r]);
; }
; __device__ __forceinline__ void finishSM(f32x16& p0, f32x16& p1, float alpha, float& l_reg, bf16x8& pa0, bf16x8& pa1, bf16x8& pa2, bf16x8& pa3) {
; #pragma unroll
;   for (int r = 0; r < 16; ++r) p1[r] = __builtin_amdgcn_exp2f(p1[r]);
;   float ps = 0;
; #pragma unroll
;   for (int r = 0; r < 16; ++r) ps += p0[r];
; #pragma unroll
;   for (int r = 0; r < 16; ++r) ps += p1[r];
;   { auto rr = __builtin_amdgcn_permlane32_swap(__float_as_uint(ps), __float_as_uint(ps), false, false);
;     ps = __uint_as_float(rr[0]) + __uint_as_float(rr[1]); }
;   l_reg = l_reg * alpha + ps;
;     ...
;   PK4(p0, 0, pa0); PK4(p0, 8, pa1); PK4(p1, 0, pa2); PK4(p1, 8, pa3);
;     ...
; }
; template <int I> __device__ __forceinline__ void pv_step(f32x16* o, int vb, const bf16x8 (&pa)[4], s16x4 (&l)[3], s16x4 (&h)[3]) {
;   if constexpr (I + 2 < 32) pv_rd<(I + 2 < 32 ? I + 2 : 0)>(vb, l[(I + 2) % 3], h[(I + 2) % 3]);
;   if constexpr (I + 2 < 32) asm volatile("s_waitcnt lgkmcnt(4)" ::: "memory"); else if constexpr (I + 1 < 32) asm volatile("s_waitcnt lgkmcnt(2)" ::: "memory"); else asm volatile("s_waitcnt lgkmcnt(0)" ::: "memory");
;   SBAR();
;   const s16x4 L = l[I % 3], H = h[I % 3];
;   o[I >> 2] = __builtin_amdgcn_mfma_f32_32x32x16_bf16(pa[I & 3], (bf16x8){L[0], L[1], L[2], L[3], H[0], H[1], H[2], H[3]}, o[I >> 2], 0, 0, 0);
;   SBAR();
;   if constexpr (I + 1 < 32) pv_step<(I + 1 < 32 ? I + 1 : 31)>(o, vb, pa, l, h);
; }
; __device__ __forceinline__ void pv_all_rolling(f32x16* o, int vb, bf16x8 pa0, bf16x8 pa1, bf16x8 pa2, bf16x8 pa3) {
;   const bf16x8 pa[4] = {pa0, pa1, pa2, pa3}; s16x4 l[3], h[3];
;   asm volatile("s_waitcnt lgkmcnt(0)" ::: "memory");
;   pv_rd<0>(vb, l[0], h[0]); pv_rd<1>(vb, l[1], h[1]);
;   pv_step<0>(o, vb, pa, l, h);
.LBB0_1440:
	v_cndmask_b32_e64 v246, v247, v246, s[6:7]
	v_mul_f32_e32 v194, 0xbe0293ee, v246
	v_fmamk_f32 v146, v146, 0x3e0293ee, v194
	v_fmamk_f32 v147, v147, 0x3e0293ee, v194
	v_fmamk_f32 v148, v148, 0x3e0293ee, v194
	v_fmamk_f32 v149, v149, 0x3e0293ee, v194
	v_fmamk_f32 v150, v150, 0x3e0293ee, v194
	v_fmamk_f32 v151, v151, 0x3e0293ee, v194
	v_fmamk_f32 v152, v152, 0x3e0293ee, v194
	v_fmamk_f32 v153, v153, 0x3e0293ee, v194
	v_fmamk_f32 v154, v154, 0x3e0293ee, v194
	v_fmamk_f32 v155, v155, 0x3e0293ee, v194
	v_fmamk_f32 v156, v156, 0x3e0293ee, v194
	v_fmamk_f32 v157, v157, 0x3e0293ee, v194
	v_fmamk_f32 v158, v158, 0x3e0293ee, v194
	v_fmamk_f32 v159, v159, 0x3e0293ee, v194
	v_fmamk_f32 v160, v160, 0x3e0293ee, v194
	v_fmamk_f32 v161, v161, 0x3e0293ee, v194
	v_fmamk_f32 v130, v130, 0x3e0293ee, v194
	v_fmamk_f32 v131, v131, 0x3e0293ee, v194
	v_fmamk_f32 v132, v132, 0x3e0293ee, v194
	v_fmamk_f32 v133, v133, 0x3e0293ee, v194
	v_fmamk_f32 v134, v134, 0x3e0293ee, v194
	v_fmamk_f32 v135, v135, 0x3e0293ee, v194
	v_fmamk_f32 v136, v136, 0x3e0293ee, v194
	v_fmamk_f32 v137, v137, 0x3e0293ee, v194
	v_fmamk_f32 v138, v138, 0x3e0293ee, v194
	v_fmamk_f32 v139, v139, 0x3e0293ee, v194
	v_fmamk_f32 v140, v140, 0x3e0293ee, v194
	v_fmamk_f32 v141, v141, 0x3e0293ee, v194
	v_fmamk_f32 v142, v142, 0x3e0293ee, v194
	v_fmamk_f32 v143, v143, 0x3e0293ee, v194
	v_fmamk_f32 v144, v144, 0x3e0293ee, v194
	v_fmac_f32_e32 v194, 0x3e0293ee, v145
	v_exp_f32_e32 v145, v146
	v_exp_f32_e32 v146, v147
	v_exp_f32_e32 v147, v148
	v_exp_f32_e32 v148, v149
	v_exp_f32_e32 v149, v150
	v_exp_f32_e32 v150, v151
	v_exp_f32_e32 v151, v152
	v_exp_f32_e32 v152, v153
	v_exp_f32_e32 v153, v154
	v_exp_f32_e32 v154, v155
	v_exp_f32_e32 v155, v156
	v_exp_f32_e32 v156, v157
	v_exp_f32_e32 v157, v158
	v_exp_f32_e32 v158, v159
	v_exp_f32_e32 v159, v160
	v_exp_f32_e32 v160, v161
	v_exp_f32_e32 v161, v130
	v_add_f32_e32 v130, 0, v145
	v_add_f32_e32 v130, v146, v130
	v_add_f32_e32 v130, v147, v130
	v_add_f32_e32 v130, v148, v130
	v_add_f32_e32 v130, v149, v130
	v_add_f32_e32 v130, v150, v130
	v_add_f32_e32 v130, v151, v130
	s_waitcnt vmcnt(0)
	s_barrier
	s_setprio 0
	v_add_f32_e32 v130, v152, v130
	v_add_f32_e32 v130, v153, v130
	v_add_f32_e32 v130, v154, v130
	v_add_f32_e32 v130, v155, v130
	v_add_f32_e32 v130, v156, v130
	v_add_f32_e32 v130, v157, v130
	v_exp_f32_e32 v195, v131
	v_add_f32_e32 v130, v158, v130
	v_exp_f32_e32 v196, v132
	v_add_f32_e32 v130, v159, v130
	v_exp_f32_e32 v197, v133
	v_add_f32_e32 v130, v160, v130
	v_exp_f32_e32 v198, v134
	v_add_f32_e32 v130, v161, v130
	v_exp_f32_e32 v199, v135
	v_add_f32_e32 v130, v195, v130
	v_exp_f32_e32 v200, v136
	v_add_f32_e32 v130, v196, v130
	v_exp_f32_e32 v201, v137
	v_add_f32_e32 v130, v197, v130
	v_exp_f32_e32 v202, v138
	v_add_f32_e32 v130, v198, v130
	v_exp_f32_e32 v203, v139
	v_add_f32_e32 v130, v199, v130
	v_exp_f32_e32 v204, v140
	v_add_f32_e32 v130, v200, v130
	v_exp_f32_e32 v205, v141
	v_add_f32_e32 v130, v201, v130
	v_exp_f32_e32 v206, v142
	v_add_f32_e32 v130, v202, v130
	v_exp_f32_e32 v207, v143
	v_add_f32_e32 v130, v203, v130
	v_exp_f32_e32 v208, v144
	v_add_f32_e32 v130, v204, v130
	v_exp_f32_e32 v194, v194
	v_add_f32_e32 v130, v205, v130
	v_add_f32_e32 v130, v206, v130
	v_add_f32_e32 v130, v207, v130
	v_add_f32_e32 v130, v208, v130
	v_add_f32_e32 v247, v194, v130
	v_mov_b32_e32 v248, v247
	s_nop 1
	v_permlane32_swap_b32_e32 v247, v248
	v_cvt_pk_bf16_f32 v130, v145, v146
	v_cvt_pk_bf16_f32 v131, v147, v148
	v_cvt_pk_bf16_f32 v132, v149, v150
	v_cvt_pk_bf16_f32 v133, v151, v152
	v_cvt_pk_bf16_f32 v134, v153, v154
	v_cvt_pk_bf16_f32 v135, v155, v156
	v_cvt_pk_bf16_f32 v136, v157, v158
	v_cvt_pk_bf16_f32 v137, v159, v160
	v_cvt_pk_bf16_f32 v138, v161, v195
	v_cvt_pk_bf16_f32 v139, v196, v197
	v_cvt_pk_bf16_f32 v140, v198, v199
	v_cvt_pk_bf16_f32 v141, v200, v201
	v_cvt_pk_bf16_f32 v142, v202, v203
	v_cvt_pk_bf16_f32 v143, v204, v205
	v_cvt_pk_bf16_f32 v144, v206, v207
	v_cvt_pk_bf16_f32 v145, v208, v194
	s_nop 0
	v_permlane32_swap_b32_e32 v130, v132
	v_permlane32_swap_b32_e32 v131, v133
	v_permlane32_swap_b32_e32 v134, v136
	v_permlane32_swap_b32_e32 v135, v137
	v_permlane32_swap_b32_e32 v138, v140
	v_permlane32_swap_b32_e32 v139, v141
	v_permlane32_swap_b32_e32 v142, v144
	v_permlane32_swap_b32_e32 v143, v145
	s_waitcnt lgkmcnt(0)
	ds_read_b64_tr_b16 v[146:147], v213 offset:0
	ds_read_b64_tr_b16 v[148:149], v213 offset:2048
	ds_read_b64_tr_b16 v[150:151], v213 offset:4096
	ds_read_b64_tr_b16 v[152:153], v213 offset:6144
	ds_read_b64_tr_b16 v[154:155], v213 offset:8192
	ds_read_b64_tr_b16 v[156:157], v213 offset:10240
	ds_read_b64_tr_b16 v[158:159], v213 offset:12288
	ds_read_b64_tr_b16 v[160:161], v213 offset:14336
	ds_read_b64_tr_b16 v[194:195], v213 offset:512
	ds_read_b64_tr_b16 v[196:197], v213 offset:2560
	v_lshl_add_u64 v[232:233], v[218:219], 0, s[22:23]
	v_lshl_add_u64 v[232:233], v[232:233], 0, s[10:11]
	s_add_i32 m0, s62, 0x8000
	s_nop 0
	global_load_lds_dwordx4 v[232:233], off
	s_waitcnt lgkmcnt(8)
	s_nop 0
	v_mfma_f32_32x32x16_bf16 v[114:129], v[130:133], v[146:149], v[114:129]
	ds_read_b64_tr_b16 v[198:199], v213 offset:4608
	ds_read_b64_tr_b16 v[200:201], v213 offset:6656
	v_lshl_add_u64 v[232:233], v[218:219], 0, s[22:23]
	v_lshl_add_u64 v[232:233], v[232:233], 0, s[12:13]
	s_add_i32 m0, s62, 0xc000
	s_nop 0
	global_load_lds_dwordx4 v[232:233], off
	s_waitcnt lgkmcnt(8)
	v_mfma_f32_32x32x16_bf16 v[114:129], v[134:137], v[150:153], v[114:129]
	ds_read_b64_tr_b16 v[202:203], v213 offset:8704
	ds_read_b64_tr_b16 v[204:205], v213 offset:10752
	v_lshl_add_u64 v[232:233], v[220:221], 0, s[22:23]
	v_lshl_add_u64 v[232:233], v[232:233], 0, s[10:11]
	s_add_i32 m0, s62, 0x8400
	s_nop 0
	global_load_lds_dwordx4 v[232:233], off
	s_waitcnt lgkmcnt(8)
; #define SBAR() __builtin_amdgcn_sched_barrier(0)
; #define DPUB() do { asm volatile("s_waitcnt vmcnt(0)" ::: "memory"); __syncthreads(); } while (0)
; #define DTILE(b) do { f32x16 p0 = f32x16{}, p1 = f32x16{}; float mn, al; bf16x8 pa0, pa1, pa2, pa3; \
;     qkt_rolling<(b) * DA_KB>(p0, p1, ka0, qr); partialSM(p0, p1, m_reg, mn, al); DRESC(al); finishSM(p0, p1, al, l_reg, pa0, pa1, pa2, pa3); SBAR(); \
;     pv_all_rolling(o, vb0 + (b) * DA_VB, pa0, pa1, pa2, pa3); } while (0)
; template <int I> __device__ __forceinline__ void pv_step(f32x16* o, int vb, const bf16x8 (&pa)[4], s16x4 (&l)[3], s16x4 (&h)[3]) {
;   if constexpr (I + 2 < 32) pv_rd<(I + 2 < 32 ? I + 2 : 0)>(vb, l[(I + 2) % 3], h[(I + 2) % 3]);
;   if constexpr (I + 2 < 32) asm volatile("s_waitcnt lgkmcnt(4)" ::: "memory"); else if constexpr (I + 1 < 32) asm volatile("s_waitcnt lgkmcnt(2)" ::: "memory"); else asm volatile("s_waitcnt lgkmcnt(0)" ::: "memory");
;   SBAR();
;   const s16x4 L = l[I % 3], H = h[I % 3];
;   o[I >> 2] = __builtin_amdgcn_mfma_f32_32x32x16_bf16(pa[I & 3], (bf16x8){L[0], L[1], L[2], L[3], H[0], H[1], H[2], H[3]}, o[I >> 2], 0, 0, 0);
;   SBAR();
;   if constexpr (I + 1 < 32) pv_step<(I + 1 < 32 ? I + 1 : 31)>(o, vb, pa, l, h);
; }
; __device__ __forceinline__ void pv_all_rolling(f32x16* o, int vb, bf16x8 pa0, bf16x8 pa1, bf16x8 pa2, bf16x8 pa3) {
;   const bf16x8 pa[4] = {pa0, pa1, pa2, pa3}; s16x4 l[3], h[3];
;   asm volatile("s_waitcnt lgkmcnt(0)" ::: "memory");
;   pv_rd<0>(vb, l[0], h[0]); pv_rd<1>(vb, l[1], h[1]);
;   pv_step<0>(o, vb, pa, l, h);
; __device__ __forceinline__ void unit_body_da(const Unit& U, char* lds) {
;     ...
;   for (int j = 0; j < NT; j += 2) {
;     DDMA(j + 1, 1); SBAR();
;     DTILE(0); SBAR(); DPUB();
;     if (j + 2 < NT) DDMA(j + 2, 0); SBAR();
;     DTILE(1); SBAR(); DPUB();
;   }
	v_mfma_f32_32x32x16_bf16 v[114:129], v[138:141], v[154:157], v[114:129]
	ds_read_b64_tr_b16 v[206:207], v213 offset:12800
	ds_read_b64_tr_b16 v[208:209], v213 offset:14848
	v_lshl_add_u64 v[232:233], v[220:221], 0, s[22:23]
	v_lshl_add_u64 v[232:233], v[232:233], 0, s[12:13]
	s_add_i32 m0, s62, 0xc400
	s_nop 0
	global_load_lds_dwordx4 v[232:233], off
	s_waitcnt lgkmcnt(8)
	v_mfma_f32_32x32x16_bf16 v[114:129], v[142:145], v[158:161], v[114:129]
	ds_read_b64_tr_b16 v[146:147], v213 offset:1024
	ds_read_b64_tr_b16 v[148:149], v213 offset:3072
	s_waitcnt lgkmcnt(8)
	v_mfma_f32_32x32x16_bf16 v[98:113], v[130:133], v[194:197], v[98:113]
	ds_read_b64_tr_b16 v[150:151], v213 offset:5120
	ds_read_b64_tr_b16 v[152:153], v213 offset:7168
	s_waitcnt lgkmcnt(8)
	v_mfma_f32_32x32x16_bf16 v[98:113], v[134:137], v[198:201], v[98:113]
	ds_read_b64_tr_b16 v[154:155], v213 offset:9216
	ds_read_b64_tr_b16 v[156:157], v213 offset:11264
	s_waitcnt lgkmcnt(8)
	v_mfma_f32_32x32x16_bf16 v[98:113], v[138:141], v[202:205], v[98:113]
	ds_read_b64_tr_b16 v[158:159], v213 offset:13312
	ds_read_b64_tr_b16 v[160:161], v213 offset:15360
	s_waitcnt lgkmcnt(8)
	v_mfma_f32_32x32x16_bf16 v[98:113], v[142:145], v[206:209], v[98:113]
	ds_read_b64_tr_b16 v[194:195], v213 offset:1536
	ds_read_b64_tr_b16 v[196:197], v213 offset:3584
	s_waitcnt lgkmcnt(8)
	v_mfma_f32_32x32x16_bf16 v[82:97], v[130:133], v[146:149], v[82:97]
	ds_read_b64_tr_b16 v[198:199], v213 offset:5632
	ds_read_b64_tr_b16 v[200:201], v213 offset:7680
	s_waitcnt lgkmcnt(8)
	v_mfma_f32_32x32x16_bf16 v[82:97], v[134:137], v[150:153], v[82:97]
	ds_read_b64_tr_b16 v[202:203], v213 offset:9728
	ds_read_b64_tr_b16 v[204:205], v213 offset:11776
	s_waitcnt lgkmcnt(8)
	v_mfma_f32_32x32x16_bf16 v[82:97], v[138:141], v[154:157], v[82:97]
	ds_read_b64_tr_b16 v[206:207], v213 offset:13824
	ds_read_b64_tr_b16 v[208:209], v213 offset:15872
	s_waitcnt lgkmcnt(8)
	v_mfma_f32_32x32x16_bf16 v[82:97], v[142:145], v[158:161], v[82:97]
	ds_read_b64_tr_b16 v[146:147], v213 offset:16384
	ds_read_b64_tr_b16 v[148:149], v213 offset:18432
	s_waitcnt lgkmcnt(8)
	v_mfma_f32_32x32x16_bf16 v[66:81], v[130:133], v[194:197], v[66:81]
	ds_read_b64_tr_b16 v[150:151], v213 offset:20480
	ds_read_b64_tr_b16 v[152:153], v213 offset:22528
	s_waitcnt lgkmcnt(8)
	v_mfma_f32_32x32x16_bf16 v[66:81], v[134:137], v[198:201], v[66:81]
	ds_read_b64_tr_b16 v[154:155], v213 offset:24576
	ds_read_b64_tr_b16 v[156:157], v213 offset:26624
	s_waitcnt lgkmcnt(8)
	v_mfma_f32_32x32x16_bf16 v[66:81], v[138:141], v[202:205], v[66:81]
	ds_read_b64_tr_b16 v[158:159], v213 offset:28672
	ds_read_b64_tr_b16 v[160:161], v213 offset:30720
	s_waitcnt lgkmcnt(8)
	v_mfma_f32_32x32x16_bf16 v[66:81], v[142:145], v[206:209], v[66:81]
	ds_read_b64_tr_b16 v[194:195], v213 offset:16896
	ds_read_b64_tr_b16 v[196:197], v213 offset:18944
	s_waitcnt lgkmcnt(8)
	v_mfma_f32_32x32x16_bf16 v[50:65], v[130:133], v[146:149], v[50:65]
	ds_read_b64_tr_b16 v[198:199], v213 offset:20992
	ds_read_b64_tr_b16 v[200:201], v213 offset:23040
	s_waitcnt lgkmcnt(8)
	v_mfma_f32_32x32x16_bf16 v[50:65], v[134:137], v[150:153], v[50:65]
	ds_read_b64_tr_b16 v[202:203], v213 offset:25088
	ds_read_b64_tr_b16 v[204:205], v213 offset:27136
	s_waitcnt lgkmcnt(8)
	v_mfma_f32_32x32x16_bf16 v[50:65], v[138:141], v[154:157], v[50:65]
	ds_read_b64_tr_b16 v[206:207], v213 offset:29184
	ds_read_b64_tr_b16 v[208:209], v213 offset:31232
	s_waitcnt lgkmcnt(8)
	v_mfma_f32_32x32x16_bf16 v[50:65], v[142:145], v[158:161], v[50:65]
	ds_read_b64_tr_b16 v[146:147], v213 offset:17408
	ds_read_b64_tr_b16 v[148:149], v213 offset:19456
	s_waitcnt lgkmcnt(8)
	v_mfma_f32_32x32x16_bf16 v[34:49], v[130:133], v[194:197], v[34:49]
	ds_read_b64_tr_b16 v[150:151], v213 offset:21504
	ds_read_b64_tr_b16 v[152:153], v213 offset:23552
	s_waitcnt lgkmcnt(8)
	v_mfma_f32_32x32x16_bf16 v[34:49], v[134:137], v[198:201], v[34:49]
	ds_read_b64_tr_b16 v[154:155], v213 offset:25600
	ds_read_b64_tr_b16 v[156:157], v213 offset:27648
	s_waitcnt lgkmcnt(8)
	v_mfma_f32_32x32x16_bf16 v[34:49], v[138:141], v[202:205], v[34:49]
	ds_read_b64_tr_b16 v[158:159], v213 offset:29696
	ds_read_b64_tr_b16 v[160:161], v213 offset:31744
	s_waitcnt lgkmcnt(8)
	v_mfma_f32_32x32x16_bf16 v[34:49], v[142:145], v[206:209], v[34:49]
	ds_read_b64_tr_b16 v[194:195], v213 offset:17920
	ds_read_b64_tr_b16 v[196:197], v213 offset:19968
	s_waitcnt lgkmcnt(8)
	v_mfma_f32_32x32x16_bf16 v[18:33], v[130:133], v[146:149], v[18:33]
	ds_read_b64_tr_b16 v[198:199], v213 offset:22016
	ds_read_b64_tr_b16 v[200:201], v213 offset:24064
	s_waitcnt lgkmcnt(8)
	v_mfma_f32_32x32x16_bf16 v[18:33], v[134:137], v[150:153], v[18:33]
	ds_read_b64_tr_b16 v[202:203], v213 offset:26112
	ds_read_b64_tr_b16 v[204:205], v213 offset:28160
	s_waitcnt lgkmcnt(8)
	v_mfma_f32_32x32x16_bf16 v[18:33], v[138:141], v[154:157], v[18:33]
	ds_read_b64_tr_b16 v[206:207], v213 offset:30208
	ds_read_b64_tr_b16 v[208:209], v213 offset:32256
	s_waitcnt lgkmcnt(8)
	v_mfma_f32_32x32x16_bf16 v[18:33], v[142:145], v[158:161], v[18:33]
	s_waitcnt lgkmcnt(6)
	v_mfma_f32_32x32x16_bf16 v[2:17], v[130:133], v[194:197], v[2:17]
	s_waitcnt lgkmcnt(4)
	v_mfma_f32_32x32x16_bf16 v[2:17], v[134:137], v[198:201], v[2:17]
	s_waitcnt lgkmcnt(2)
	v_mfma_f32_32x32x16_bf16 v[2:17], v[138:141], v[202:205], v[2:17]
	s_waitcnt lgkmcnt(0)
	v_mfma_f32_32x32x16_bf16 v[2:17], v[142:145], v[206:209], v[2:17]
	s_waitcnt vmcnt(0)
	s_cmp_ge_u32 s80, s96
	s_cselect_b64 s[24:25], -1, 0
	s_and_b64 vcc, exec, s[24:25]
	s_waitcnt vmcnt(0) lgkmcnt(0)
	s_barrier
; #define SBAR() __builtin_amdgcn_sched_barrier(0)
; template <int OFF> __device__ __forceinline__ bf16x8 k_read(int a) { bf16x8 r; asm volatile("ds_read_b128 %0, %1 offset:%2" : "=&v"(r) : "v"(a), "i"(OFF) : "memory"); return r; }
; __device__ __forceinline__ void partialSM(f32x16& p0, f32x16& p1, float& m_reg, float& mn, float& alpha) {
;   constexpr float C = SCALE * 1.4426950408889634f;
;   float pmax = p0[0];
; #pragma unroll
;   for (int r = 1; r < 16; ++r) pmax = fmaxf(pmax, p0[r]);
; #pragma unroll
;   for (int r = 0; r < 16; ++r) pmax = fmaxf(pmax, p1[r]);
;   { auto rr = __builtin_amdgcn_permlane32_swap(__float_as_uint(pmax), __float_as_uint(pmax), false, false);
;     pmax = fmaxf(__uint_as_float(rr[0]), __uint_as_float(rr[1])); }
;   if (__builtin_expect(__all(pmax - m_reg <= THR / SCALE), 1)) { mn = m_reg; alpha = 1.f; }
;   else { mn = fmaxf(m_reg, pmax); alpha = __builtin_amdgcn_exp2f((m_reg - mn) * C); m_reg = mn; }
; template <int BUFOFF, int D0> __device__ __forceinline__ void qk_step(f32x16& p0, f32x16& p1, int ka0, const bf16x8 (&qr)[8], bf16x8 (&k0)[2], bf16x8 (&k1)[2]) {
;   if constexpr (D0 + 1 < 8) { const int a_ = ka0 ^ ((D0 + 1) << 5); k0[(D0 + 1) & 1] = k_read<BUFOFF>(a_); k1[(D0 + 1) & 1] = k_read<BUFOFF + 8192>(a_); }
;   if constexpr (D0 + 1 < 8) asm volatile("s_waitcnt lgkmcnt(2)" ::: "memory"); else asm volatile("s_waitcnt lgkmcnt(0)" ::: "memory");
;   SBAR();
;   p0 = __builtin_amdgcn_mfma_f32_32x32x16_bf16(k0[D0 & 1], qr[D0], p0, 0, 0, 0);
;   p1 = __builtin_amdgcn_mfma_f32_32x32x16_bf16(k1[D0 & 1], qr[D0], p1, 0, 0, 0);
;   SBAR();
;   if constexpr (D0 + 1 < 8) qk_step<BUFOFF, (D0 + 1 < 8 ? D0 + 1 : 7)>(p0, p1, ka0, qr, k0, k1);
; }
; template <int BUFOFF> __device__ __forceinline__ void qkt_rolling(f32x16& p0, f32x16& p1, int ka0, const bf16x8 (&qr)[8]) {
;   bf16x8 k0[2], k1[2];
;   asm volatile("s_waitcnt lgkmcnt(0)" ::: "memory");
;   k0[0] = k_read<BUFOFF>(ka0); k1[0] = k_read<BUFOFF + 8192>(ka0);
;   qk_step<BUFOFF, 0>(p0, p1, ka0, qr, k0, k1);
; }
.LBB0_1442:
	s_setprio 1
	s_waitcnt lgkmcnt(0)
	ds_read_b128 v[194:197], v235 offset:16384
	ds_read_b128 v[198:201], v236 offset:16384
	ds_read_b128 v[202:205], v238 offset:16384
	ds_read_b128 v[206:209], v239 offset:16384
	ds_read_b128 v[130:133], v240 offset:16384
	ds_read_b128 v[134:137], v241 offset:16384
	ds_read_b128 v[138:141], v242 offset:16384
	ds_read_b128 v[142:145], v243 offset:16384
	v_lshl_add_u64 v[232:233], v[224:225], 0, s[14:15]
	s_mov_b32 m0, s61
	s_nop 0
	global_load_lds_dwordx4 v[232:233], off
	v_lshl_add_u64 v[232:233], v[228:229], 0, s[14:15]
	s_mov_b32 m0, s67
	s_nop 0
	global_load_lds_dwordx4 v[232:233], off
	s_waitcnt lgkmcnt(7)
	s_nop 0
	v_mfma_f32_32x32x16_bf16 v[146:161], v[194:197], v[162:165], 0
	ds_read_b128 v[194:197], v235 offset:24576
	s_waitcnt lgkmcnt(7)
	v_mfma_f32_32x32x16_bf16 v[146:161], v[198:201], v[166:169], v[146:161]
	ds_read_b128 v[198:201], v236 offset:24576
	s_waitcnt lgkmcnt(7)
	v_mfma_f32_32x32x16_bf16 v[146:161], v[202:205], v[170:173], v[146:161]
	ds_read_b128 v[202:205], v238 offset:24576
	s_waitcnt lgkmcnt(7)
	v_mfma_f32_32x32x16_bf16 v[146:161], v[206:209], v[174:177], v[146:161]
	ds_read_b128 v[206:209], v239 offset:24576
	s_waitcnt lgkmcnt(7)
	v_mfma_f32_32x32x16_bf16 v[146:161], v[130:133], v[178:181], v[146:161]
	s_waitcnt lgkmcnt(6)
	v_mfma_f32_32x32x16_bf16 v[146:161], v[134:137], v[182:185], v[146:161]
	s_waitcnt lgkmcnt(5)
	v_mfma_f32_32x32x16_bf16 v[146:161], v[138:141], v[186:189], v[146:161]
	s_waitcnt lgkmcnt(4)
	v_mfma_f32_32x32x16_bf16 v[146:161], v[142:145], v[190:193], v[146:161]
	s_waitcnt lgkmcnt(3)
	v_mfma_f32_32x32x16_bf16 v[130:145], v[194:197], v[162:165], 0
	ds_read_b128 v[194:197], v240 offset:24576
	s_waitcnt lgkmcnt(3)
	v_mfma_f32_32x32x16_bf16 v[130:145], v[198:201], v[166:169], v[130:145]
	ds_read_b128 v[198:201], v241 offset:24576
	s_waitcnt lgkmcnt(3)
	v_mfma_f32_32x32x16_bf16 v[130:145], v[202:205], v[170:173], v[130:145]
	ds_read_b128 v[202:205], v242 offset:24576
	s_waitcnt lgkmcnt(3)
	v_mfma_f32_32x32x16_bf16 v[130:145], v[206:209], v[174:177], v[130:145]
	ds_read_b128 v[206:209], v243 offset:24576
	s_waitcnt lgkmcnt(3)
	v_mfma_f32_32x32x16_bf16 v[130:145], v[194:197], v[178:181], v[130:145]
	s_waitcnt lgkmcnt(2)
	v_mfma_f32_32x32x16_bf16 v[130:145], v[198:201], v[182:185], v[130:145]
	s_waitcnt lgkmcnt(1)
	v_mfma_f32_32x32x16_bf16 v[130:145], v[202:205], v[186:189], v[130:145]
	s_waitcnt lgkmcnt(0)
	v_mfma_f32_32x32x16_bf16 v[130:145], v[206:209], v[190:193], v[130:145]
	s_setprio 0
	v_max3_f32 v194, v146, v147, v148
	v_max3_f32 v195, v154, v155, v156
	v_max3_f32 v194, v194, v149, v150
	v_max3_f32 v195, v195, v157, v158
	v_max3_f32 v194, v194, v151, v152
	v_max3_f32 v195, v195, v159, v160
	v_max_f32_e32 v194, v194, v153
	v_max_f32_e32 v195, v195, v161
	s_nop 4
	v_max3_f32 v196, v130, v131, v132
	v_max3_f32 v197, v138, v139, v140
	v_max3_f32 v196, v196, v133, v134
	v_max3_f32 v197, v197, v141, v142
	v_max3_f32 v196, v196, v135, v136
	v_max3_f32 v197, v197, v143, v144
	v_max_f32_e32 v196, v196, v137
	v_max_f32_e32 v197, v197, v145
	v_max3_f32 v194, v194, v195, v196
	v_max_f32_e32 v194, v194, v197
	v_mov_b32_e32 v195, v194
	s_nop 1
	v_permlane32_swap_b32_e32 v194, v195
	v_max_f32_e32 v194, v194, v195
	v_sub_f32_e32 v195, v194, v246
	v_cmp_ge_f32_e32 vcc, s95, v195
	s_cmp_eq_u64 vcc, exec
	s_cbranch_scc0 .Lda_slow_l1_2
	s_mov_b64 s[6:7], -1
	v_mov_b32_e32 v222, 1.0
	s_branch .LBB0_1435
.Lda_slow_l1_2:
	v_max_f32_e32 v223, v246, v194
	v_sub_f32_e32 v194, v246, v223
	v_mul_f32_e32 v194, 0x3e0293ee, v194
	v_exp_f32_e32 v194, v194
	s_mov_b64 s[6:7], 0
	s_nop 0
	v_mov_b32_e32 v222, v194
	v_cmp_gt_f32_e32 vcc, 1.0, v222
	s_cbranch_vccz .LBB0_1435
	s_and_saveexec_b64 s[56:57], s[0:1]
	s_cbranch_execz .LBB0_1434
	ds_write_b32 v237, v222 offset:128
	s_branch .LBB0_1434
